# remaining in-loop LDS-DMA loads of 5 GEMMs use scalar bases (kstep-advanced base kept in spare SGPR pairs); 12 of 16 per-iteration VALU address adds gone
# speedup vs baseline: 1.0081x; 1.0042x over previous
; #define PG8_STAGE(bufoff, gbase, voff) do { _Pragma("unroll") for (int _i = 0; _i < 2; ++_i) \
;         __builtin_amdgcn_global_load_lds((const unsigned*)((const char*)(gbase) + (voff)[_i]), (LAS unsigned*)(lds + (bufoff) + ldsw + _i * 8192), 16, 0, 0); } while (0)
; #define PG8_LDA(dst, b, h) do { _Pragma("unroll") for (int m = 0; m < 4; ++m) _Pragma("unroll") for (int k = 0; k < 2; ++k) dst[m][k] = *(const LAS bf16x8*)(lds + PG8_SA(b, h) + aoff + m * 2048 + k * 1024); } while (0)
; #define PG8_LDB(dst, b, h) do { _Pragma("unroll") for (int n = 0; n < 2; ++n) _Pragma("unroll") for (int k = 0; k < 2; ++k) dst[n][k] = *(const LAS bf16x8*)(lds + PG8_SB(b, h) + boff + n * 2048 + k * 1024); } while (0)
; #define PG8_MMA(ai, bj, At, Bt) do { __builtin_amdgcn_s_setprio(1); _Pragma("unroll") for (int m = 0; m < 4; ++m) _Pragma("unroll") for (int n = 0; n < 2; ++n) _Pragma("unroll") for (int k = 0; k < 2; ++k) \
;         acc[ai][bj][m][n] = __builtin_amdgcn_mfma_f32_16x16x32_bf16(Bt[n][k], At[m][k], acc[ai][bj][m][n], 0, 0, 0); __builtin_amdgcn_s_setprio(0); } while (0)
; #define PG8_WAIT_V(n) asm volatile("s_waitcnt vmcnt(" #n ")" ::: "memory")
; #define PG8_WAIT_L(n) asm volatile("s_waitcnt lgkmcnt(" #n ")" ::: "memory")
; #define PG8_BAR __builtin_amdgcn_s_barrier()
; #define PG8_SCHED __builtin_amdgcn_sched_barrier(0)
; template <class Epi, class Sched, bool AREMAP>
; __device__ __forceinline__ void gemm_phase(LAS unsigned char* lds, const Gemm g, const Sched& S, const Epi& E, int wv) {
;     ...
;             PG8_LDB(B0, 0, 0); PG8_SCHED; PG8_LDA(At, 0, 0); PG8_STAGE(PG8_SA(1, 1), a1 + hstepA, voffA);
;             PG8_WAIT_L(8); PG8_BAR; PG8_WAIT_L(0); PG8_MMA(0, 0, At, B0); PG8_BAR; PG8_SCHED;
;             PG8_LDB(B1, 0, 1); PG8_STAGE(PG8_SB(0, 0), b2, voffB);
;             PG8_BAR; PG8_WAIT_L(0); PG8_MMA(0, 1, At, B1); PG8_BAR;
;             PG8_LDA(At, 0, 1); PG8_STAGE(PG8_SA(0, 0), a2, voffA);
;             PG8_BAR; PG8_WAIT_L(0); PG8_MMA(1, 0, At, B0); PG8_BAR; PG8_SCHED;
;             PG8_STAGE(PG8_SB(0, 1), b2 + hstepB, voffB);
;             PG8_WAIT_V(6); PG8_BAR; PG8_MMA(1, 1, At, B1); PG8_BAR;
.LBB0_202:
	s_add_u32 s18, s16, 0xfff80080
	s_addc_u32 s19, s17, -1
	s_add_i32 s38, 0, 0x10000
	v_add_u32_e32 v145, s38, v142
	ds_read_b128 v[146:149], v145
	ds_read_b128 v[150:153], v145 offset:1024
	ds_read_b128 v[154:157], v145 offset:2048
	ds_read_b128 v[158:161], v145 offset:3072
	s_cmp_eq_u32 s56, 28
	s_cselect_b32 s21, s11, s19
	s_cselect_b32 s20, s47, s18
	s_cselect_b32 s19, s9, s55
	s_cselect_b32 s18, s52, s53
	s_add_i32 m0, s7, 0xc000
	ds_read_b128 v[162:165], v144
	ds_read_b128 v[166:169], v144 offset:1024
	ds_read_b128 v[170:173], v144 offset:2048
	ds_read_b128 v[174:177], v144 offset:3072
	ds_read_b128 v[178:181], v144 offset:4096
	ds_read_b128 v[182:185], v144 offset:5120
	ds_read_b128 v[196:199], v144 offset:6144
	ds_read_b128 v[200:203], v144 offset:7168
	global_load_lds_dwordx4 v140, s[16:17]
	s_add_i32 m0, s7, 0xe000
	s_nop 0
	global_load_lds_dwordx4 v138, s[16:17]
	s_waitcnt lgkmcnt(8)
	s_barrier
	s_waitcnt lgkmcnt(0)
	s_waitcnt lgkmcnt(0)
	v_mfma_f32_16x16x32_bf16 v[126:129], v[146:149], v[162:165], v[126:129]
	v_mfma_f32_16x16x32_bf16 v[122:125], v[154:157], v[162:165], v[122:125]
	v_mfma_f32_16x16x32_bf16 v[118:121], v[146:149], v[170:173], v[118:121]
	v_mfma_f32_16x16x32_bf16 v[114:117], v[154:157], v[170:173], v[114:117]
	v_mfma_f32_16x16x32_bf16 v[102:105], v[146:149], v[178:181], v[102:105]
	v_mfma_f32_16x16x32_bf16 v[98:101], v[154:157], v[178:181], v[98:101]
	v_mfma_f32_16x16x32_bf16 v[86:89], v[146:149], v[196:199], v[86:89]
	v_mfma_f32_16x16x32_bf16 v[82:85], v[154:157], v[196:199], v[82:85]
	v_mfma_f32_16x16x32_bf16 v[126:129], v[150:153], v[166:169], v[126:129]
	v_mfma_f32_16x16x32_bf16 v[122:125], v[158:161], v[166:169], v[122:125]
	v_mfma_f32_16x16x32_bf16 v[118:121], v[150:153], v[174:177], v[118:121]
	v_mfma_f32_16x16x32_bf16 v[114:117], v[158:161], v[174:177], v[114:117]
	v_mfma_f32_16x16x32_bf16 v[102:105], v[150:153], v[182:185], v[102:105]
	v_mfma_f32_16x16x32_bf16 v[98:101], v[158:161], v[182:185], v[98:101]
	v_mfma_f32_16x16x32_bf16 v[86:89], v[150:153], v[200:203], v[86:89]
	v_mfma_f32_16x16x32_bf16 v[82:85], v[158:161], v[200:203], v[82:85]
	s_barrier
	s_add_i32 s39, 0, 0x14000
	s_add_i32 s38, s38, s29
	v_add_u32_e32 v145, s39, v142
	s_add_u32 s80, s18, 0x80
	s_addc_u32 s81, s19, 0
	s_mov_b32 m0, s38
	ds_read_b128 v[204:207], v145
	ds_read_b128 v[208:211], v145 offset:1024
	ds_read_b128 v[212:215], v145 offset:2048
	ds_read_b128 v[216:219], v145 offset:3072
	global_load_lds_dwordx4 v132, s[18:19]
	s_add_i32 m0, s38, 0x2000
	s_nop 0
	global_load_lds_dwordx4 v136, s[18:19]
	s_barrier
	s_waitcnt lgkmcnt(0)
	s_waitcnt lgkmcnt(0)
	v_mfma_f32_16x16x32_bf16 v[110:113], v[204:207], v[162:165], v[110:113]
	v_mfma_f32_16x16x32_bf16 v[106:109], v[212:215], v[162:165], v[106:109]
	v_mfma_f32_16x16x32_bf16 v[94:97], v[204:207], v[170:173], v[94:97]
	v_mfma_f32_16x16x32_bf16 v[90:93], v[212:215], v[170:173], v[90:93]
	v_mfma_f32_16x16x32_bf16 v[78:81], v[204:207], v[178:181], v[78:81]
	v_mfma_f32_16x16x32_bf16 v[74:77], v[212:215], v[178:181], v[74:77]
	v_mfma_f32_16x16x32_bf16 v[70:73], v[204:207], v[196:199], v[70:73]
	v_mfma_f32_16x16x32_bf16 v[66:69], v[212:215], v[196:199], v[66:69]
	v_mfma_f32_16x16x32_bf16 v[110:113], v[208:211], v[166:169], v[110:113]
	v_mfma_f32_16x16x32_bf16 v[106:109], v[216:219], v[166:169], v[106:109]
	v_mfma_f32_16x16x32_bf16 v[94:97], v[208:211], v[174:177], v[94:97]
	v_mfma_f32_16x16x32_bf16 v[90:93], v[216:219], v[174:177], v[90:93]
	v_mfma_f32_16x16x32_bf16 v[78:81], v[208:211], v[182:185], v[78:81]
	v_mfma_f32_16x16x32_bf16 v[74:77], v[216:219], v[182:185], v[74:77]
	v_mfma_f32_16x16x32_bf16 v[70:73], v[208:211], v[200:203], v[70:73]
	v_mfma_f32_16x16x32_bf16 v[66:69], v[216:219], v[200:203], v[66:69]
	s_mov_b32 m0, s7
	s_add_u32 s96, s20, 0x80
	s_addc_u32 s97, s21, 0
	s_barrier
	ds_read_b128 v[162:165], v144 offset:16384
	ds_read_b128 v[166:169], v144 offset:17408
	ds_read_b128 v[170:173], v144 offset:18432
	ds_read_b128 v[174:177], v144 offset:19456
	ds_read_b128 v[178:181], v144 offset:20480
	ds_read_b128 v[182:185], v144 offset:21504
	ds_read_b128 v[196:199], v144 offset:22528
	ds_read_b128 v[200:203], v144 offset:23552
	global_load_lds_dwordx4 v130, s[20:21]
	s_mov_b32 m0, s30
	s_nop 0
	global_load_lds_dwordx4 v134, s[20:21]
	s_barrier
	s_waitcnt lgkmcnt(0)
	s_waitcnt lgkmcnt(0)
	v_mfma_f32_16x16x32_bf16 v[62:65], v[146:149], v[162:165], v[62:65]
	v_mfma_f32_16x16x32_bf16 v[58:61], v[154:157], v[162:165], v[58:61]
	v_mfma_f32_16x16x32_bf16 v[54:57], v[146:149], v[170:173], v[54:57]
	v_mfma_f32_16x16x32_bf16 v[50:53], v[154:157], v[170:173], v[50:53]
	v_mfma_f32_16x16x32_bf16 v[38:41], v[146:149], v[178:181], v[38:41]
	v_mfma_f32_16x16x32_bf16 v[34:37], v[154:157], v[178:181], v[34:37]
	v_mfma_f32_16x16x32_bf16 v[22:25], v[146:149], v[196:199], v[22:25]
	v_mfma_f32_16x16x32_bf16 v[18:21], v[154:157], v[196:199], v[18:21]
	v_mfma_f32_16x16x32_bf16 v[62:65], v[150:153], v[166:169], v[62:65]
	v_mfma_f32_16x16x32_bf16 v[58:61], v[158:161], v[166:169], v[58:61]
	v_mfma_f32_16x16x32_bf16 v[54:57], v[150:153], v[174:177], v[54:57]
	v_mfma_f32_16x16x32_bf16 v[50:53], v[158:161], v[174:177], v[50:53]
	v_mfma_f32_16x16x32_bf16 v[38:41], v[150:153], v[182:185], v[38:41]
	v_mfma_f32_16x16x32_bf16 v[34:37], v[158:161], v[182:185], v[34:37]
	v_mfma_f32_16x16x32_bf16 v[22:25], v[150:153], v[200:203], v[22:25]
	v_mfma_f32_16x16x32_bf16 v[18:21], v[158:161], v[200:203], v[18:21]
	s_barrier
	s_add_u32 s62, s18, 0x80000
	s_addc_u32 s63, s19, 0
	s_add_i32 s38, s39, s29
	s_mov_b32 m0, s38
	s_nop 0
	global_load_lds_dwordx4 v132, s[62:63]
	s_add_i32 m0, s38, 0x2000
	s_nop 0
	global_load_lds_dwordx4 v136, s[62:63]
	s_waitcnt vmcnt(6)
	s_barrier
; #define PG8_STAGE(bufoff, gbase, voff) do { _Pragma("unroll") for (int _i = 0; _i < 2; ++_i) \
;         __builtin_amdgcn_global_load_lds((const unsigned*)((const char*)(gbase) + (voff)[_i]), (LAS unsigned*)(lds + (bufoff) + ldsw + _i * 8192), 16, 0, 0); } while (0)
; #define PG8_LDA(dst, b, h) do { _Pragma("unroll") for (int m = 0; m < 4; ++m) _Pragma("unroll") for (int k = 0; k < 2; ++k) dst[m][k] = *(const LAS bf16x8*)(lds + PG8_SA(b, h) + aoff + m * 2048 + k * 1024); } while (0)
; #define PG8_LDB(dst, b, h) do { _Pragma("unroll") for (int n = 0; n < 2; ++n) _Pragma("unroll") for (int k = 0; k < 2; ++k) dst[n][k] = *(const LAS bf16x8*)(lds + PG8_SB(b, h) + boff + n * 2048 + k * 1024); } while (0)
; #define PG8_MMA(ai, bj, At, Bt) do { __builtin_amdgcn_s_setprio(1); _Pragma("unroll") for (int m = 0; m < 4; ++m) _Pragma("unroll") for (int n = 0; n < 2; ++n) _Pragma("unroll") for (int k = 0; k < 2; ++k) \
;         acc[ai][bj][m][n] = __builtin_amdgcn_mfma_f32_16x16x32_bf16(Bt[n][k], At[m][k], acc[ai][bj][m][n], 0, 0, 0); __builtin_amdgcn_s_setprio(0); } while (0)
; #define PG8_WAIT_V(n) asm volatile("s_waitcnt vmcnt(" #n ")" ::: "memory")
; #define PG8_WAIT_L(n) asm volatile("s_waitcnt lgkmcnt(" #n ")" ::: "memory")
; #define PG8_BAR __builtin_amdgcn_s_barrier()
; #define PG8_SCHED __builtin_amdgcn_sched_barrier(0)
; template <class Epi, class Sched, bool AREMAP>
; __device__ __forceinline__ void gemm_phase(LAS unsigned char* lds, const Gemm g, const Sched& S, const Epi& E, int wv) {
;     ...
;             PG8_WAIT_V(6); PG8_BAR; PG8_MMA(1, 1, At, B1); PG8_BAR;
;             PG8_LDB(B0, 1, 0); PG8_SCHED; PG8_LDA(At, 1, 0); PG8_STAGE(PG8_SA(0, 1), a2 + hstepA, voffA);
;             PG8_WAIT_L(8); PG8_BAR; PG8_WAIT_L(0); PG8_MMA(0, 0, At, B0); PG8_BAR; PG8_SCHED;
;             PG8_LDB(B1, 1, 1); PG8_STAGE(PG8_SB(1, 0), b3, voffB);
;             PG8_BAR; PG8_WAIT_L(0); PG8_MMA(0, 1, At, B1); PG8_BAR;
;             PG8_LDA(At, 1, 1); PG8_STAGE(PG8_SA(1, 0), a3, voffA);
	v_mfma_f32_16x16x32_bf16 v[46:49], v[204:207], v[162:165], v[46:49]
	v_mfma_f32_16x16x32_bf16 v[42:45], v[212:215], v[162:165], v[42:45]
	v_mfma_f32_16x16x32_bf16 v[30:33], v[204:207], v[170:173], v[30:33]
	v_mfma_f32_16x16x32_bf16 v[26:29], v[212:215], v[170:173], v[26:29]
	v_mfma_f32_16x16x32_bf16 v[14:17], v[204:207], v[178:181], v[14:17]
	v_mfma_f32_16x16x32_bf16 v[10:13], v[212:215], v[178:181], v[10:13]
	v_mfma_f32_16x16x32_bf16 v[6:9], v[204:207], v[196:199], v[6:9]
	v_mfma_f32_16x16x32_bf16 v[2:5], v[212:215], v[196:199], v[2:5]
	v_mfma_f32_16x16x32_bf16 v[46:49], v[208:211], v[166:169], v[46:49]
	v_mfma_f32_16x16x32_bf16 v[42:45], v[216:219], v[166:169], v[42:45]
	v_mfma_f32_16x16x32_bf16 v[30:33], v[208:211], v[174:177], v[30:33]
	v_mfma_f32_16x16x32_bf16 v[26:29], v[216:219], v[174:177], v[26:29]
	v_mfma_f32_16x16x32_bf16 v[14:17], v[208:211], v[182:185], v[14:17]
	v_mfma_f32_16x16x32_bf16 v[10:13], v[216:219], v[182:185], v[10:13]
	v_mfma_f32_16x16x32_bf16 v[6:9], v[208:211], v[200:203], v[6:9]
	v_mfma_f32_16x16x32_bf16 v[2:5], v[216:219], v[200:203], v[2:5]
	s_add_i32 s38, 0, 0x18000
	v_add_u32_e32 v145, s38, v142
	s_barrier
	ds_read_b128 v[146:149], v145
	ds_read_b128 v[150:153], v145 offset:1024
	ds_read_b128 v[154:157], v145 offset:2048
	ds_read_b128 v[158:161], v145 offset:3072
	s_add_u32 s20, s20, 0x80000
	s_addc_u32 s21, s21, 0
	s_mov_b32 m0, s31
	ds_read_b128 v[162:165], v144 offset:32768
	ds_read_b128 v[166:169], v144 offset:33792
	ds_read_b128 v[170:173], v144 offset:34816
	ds_read_b128 v[174:177], v144 offset:35840
	ds_read_b128 v[178:181], v144 offset:36864
	ds_read_b128 v[182:185], v144 offset:37888
	ds_read_b128 v[196:199], v144 offset:38912
	ds_read_b128 v[200:203], v144 offset:39936
	global_load_lds_dwordx4 v130, s[20:21]
	s_mov_b32 m0, s34
	s_nop 0
	global_load_lds_dwordx4 v134, s[20:21]
	s_waitcnt lgkmcnt(8)
	s_barrier
	s_waitcnt lgkmcnt(0)
	s_waitcnt lgkmcnt(0)
	v_mfma_f32_16x16x32_bf16 v[126:129], v[146:149], v[162:165], v[126:129]
	v_mfma_f32_16x16x32_bf16 v[122:125], v[154:157], v[162:165], v[122:125]
	v_mfma_f32_16x16x32_bf16 v[118:121], v[146:149], v[170:173], v[118:121]
	v_mfma_f32_16x16x32_bf16 v[114:117], v[154:157], v[170:173], v[114:117]
	v_mfma_f32_16x16x32_bf16 v[102:105], v[146:149], v[178:181], v[102:105]
	v_mfma_f32_16x16x32_bf16 v[98:101], v[154:157], v[178:181], v[98:101]
	v_mfma_f32_16x16x32_bf16 v[86:89], v[146:149], v[196:199], v[86:89]
	v_mfma_f32_16x16x32_bf16 v[82:85], v[154:157], v[196:199], v[82:85]
	v_mfma_f32_16x16x32_bf16 v[126:129], v[150:153], v[166:169], v[126:129]
	v_mfma_f32_16x16x32_bf16 v[122:125], v[158:161], v[166:169], v[122:125]
	v_mfma_f32_16x16x32_bf16 v[118:121], v[150:153], v[174:177], v[118:121]
	v_mfma_f32_16x16x32_bf16 v[114:117], v[158:161], v[174:177], v[114:117]
	v_mfma_f32_16x16x32_bf16 v[102:105], v[150:153], v[182:185], v[102:105]
	v_mfma_f32_16x16x32_bf16 v[98:101], v[158:161], v[182:185], v[98:101]
	v_mfma_f32_16x16x32_bf16 v[86:89], v[150:153], v[200:203], v[86:89]
	v_mfma_f32_16x16x32_bf16 v[82:85], v[158:161], v[200:203], v[82:85]
	s_barrier
	s_add_i32 s20, 0, 0x1c000
	s_add_i32 s21, s38, s29
	v_add_u32_e32 v145, s20, v142
	s_mov_b32 m0, s21
	ds_read_b128 v[204:207], v145
	ds_read_b128 v[208:211], v145 offset:1024
	ds_read_b128 v[212:215], v145 offset:2048
	ds_read_b128 v[216:219], v145 offset:3072
	global_load_lds_dwordx4 v132, s[80:81]
	s_add_i32 m0, s21, 0x2000
	s_nop 0
	global_load_lds_dwordx4 v136, s[80:81]
	s_barrier
	s_waitcnt lgkmcnt(0)
	s_waitcnt lgkmcnt(0)
	v_mfma_f32_16x16x32_bf16 v[110:113], v[204:207], v[162:165], v[110:113]
	v_mfma_f32_16x16x32_bf16 v[106:109], v[212:215], v[162:165], v[106:109]
	v_mfma_f32_16x16x32_bf16 v[94:97], v[204:207], v[170:173], v[94:97]
	v_mfma_f32_16x16x32_bf16 v[90:93], v[212:215], v[170:173], v[90:93]
	v_mfma_f32_16x16x32_bf16 v[78:81], v[204:207], v[178:181], v[78:81]
	v_mfma_f32_16x16x32_bf16 v[74:77], v[212:215], v[178:181], v[74:77]
	v_mfma_f32_16x16x32_bf16 v[70:73], v[204:207], v[196:199], v[70:73]
	v_mfma_f32_16x16x32_bf16 v[66:69], v[212:215], v[196:199], v[66:69]
	v_mfma_f32_16x16x32_bf16 v[110:113], v[208:211], v[166:169], v[110:113]
	v_mfma_f32_16x16x32_bf16 v[106:109], v[216:219], v[166:169], v[106:109]
	v_mfma_f32_16x16x32_bf16 v[94:97], v[208:211], v[174:177], v[94:97]
	v_mfma_f32_16x16x32_bf16 v[90:93], v[216:219], v[174:177], v[90:93]
	v_mfma_f32_16x16x32_bf16 v[78:81], v[208:211], v[182:185], v[78:81]
	v_mfma_f32_16x16x32_bf16 v[74:77], v[216:219], v[182:185], v[74:77]
	v_mfma_f32_16x16x32_bf16 v[70:73], v[208:211], v[200:203], v[70:73]
	v_mfma_f32_16x16x32_bf16 v[66:69], v[216:219], v[200:203], v[66:69]
	s_mov_b32 m0, s35
	s_barrier
	ds_read_b128 v[162:165], v144 offset:49152
	ds_read_b128 v[166:169], v144 offset:50176
	ds_read_b128 v[170:173], v144 offset:51200
	ds_read_b128 v[174:177], v144 offset:52224
	ds_read_b128 v[178:181], v144 offset:53248
	ds_read_b128 v[182:185], v144 offset:54272
	ds_read_b128 v[196:199], v144 offset:55296
	ds_read_b128 v[200:203], v144 offset:56320
	global_load_lds_dwordx4 v130, s[96:97]
	s_mov_b32 m0, s36
	s_nop 0
	global_load_lds_dwordx4 v134, s[96:97]
	s_barrier
; #define PG8_STAGE(bufoff, gbase, voff) do { _Pragma("unroll") for (int _i = 0; _i < 2; ++_i) \
;         __builtin_amdgcn_global_load_lds((const unsigned*)((const char*)(gbase) + (voff)[_i]), (LAS unsigned*)(lds + (bufoff) + ldsw + _i * 8192), 16, 0, 0); } while (0)
; #define PG8_MMA(ai, bj, At, Bt) do { __builtin_amdgcn_s_setprio(1); _Pragma("unroll") for (int m = 0; m < 4; ++m) _Pragma("unroll") for (int n = 0; n < 2; ++n) _Pragma("unroll") for (int k = 0; k < 2; ++k) \
;         acc[ai][bj][m][n] = __builtin_amdgcn_mfma_f32_16x16x32_bf16(Bt[n][k], At[m][k], acc[ai][bj][m][n], 0, 0, 0); __builtin_amdgcn_s_setprio(0); } while (0)
; #define PG8_WAIT_V(n) asm volatile("s_waitcnt vmcnt(" #n ")" ::: "memory")
; #define PG8_WAIT_L(n) asm volatile("s_waitcnt lgkmcnt(" #n ")" ::: "memory")
; #define PG8_BAR __builtin_amdgcn_s_barrier()
; #define PG8_SCHED __builtin_amdgcn_sched_barrier(0)
; template <class Epi, class Sched, bool AREMAP>
; __device__ __forceinline__ void gemm_phase(LAS unsigned char* lds, const Gemm g, const Sched& S, const Epi& E, int wv) {
;     ...
;             PG8_BAR; PG8_WAIT_L(0); PG8_MMA(1, 0, At, B0); PG8_BAR; PG8_SCHED;
;             PG8_STAGE(PG8_SB(1, 1), b3 + hstepB, voffB);
;             PG8_WAIT_V(6); PG8_BAR; PG8_MMA(1, 1, At, B1); PG8_BAR;
	s_waitcnt lgkmcnt(0)
	s_waitcnt lgkmcnt(0)
	v_mfma_f32_16x16x32_bf16 v[62:65], v[146:149], v[162:165], v[62:65]
	v_mfma_f32_16x16x32_bf16 v[58:61], v[154:157], v[162:165], v[58:61]
	v_mfma_f32_16x16x32_bf16 v[54:57], v[146:149], v[170:173], v[54:57]
	v_mfma_f32_16x16x32_bf16 v[50:53], v[154:157], v[170:173], v[50:53]
	v_mfma_f32_16x16x32_bf16 v[38:41], v[146:149], v[178:181], v[38:41]
	v_mfma_f32_16x16x32_bf16 v[34:37], v[154:157], v[178:181], v[34:37]
	v_mfma_f32_16x16x32_bf16 v[22:25], v[146:149], v[196:199], v[22:25]
	v_mfma_f32_16x16x32_bf16 v[18:21], v[154:157], v[196:199], v[18:21]
	v_mfma_f32_16x16x32_bf16 v[62:65], v[150:153], v[166:169], v[62:65]
	v_mfma_f32_16x16x32_bf16 v[58:61], v[158:161], v[166:169], v[58:61]
	v_mfma_f32_16x16x32_bf16 v[54:57], v[150:153], v[174:177], v[54:57]
	v_mfma_f32_16x16x32_bf16 v[50:53], v[158:161], v[174:177], v[50:53]
	v_mfma_f32_16x16x32_bf16 v[38:41], v[150:153], v[182:185], v[38:41]
	v_mfma_f32_16x16x32_bf16 v[34:37], v[158:161], v[182:185], v[34:37]
	v_mfma_f32_16x16x32_bf16 v[22:25], v[150:153], v[200:203], v[22:25]
	v_mfma_f32_16x16x32_bf16 v[18:21], v[158:161], v[200:203], v[18:21]
	s_barrier
	s_add_u32 s18, s18, 0x80080
	s_addc_u32 s19, s19, 0
	s_add_i32 s20, s20, s29
	s_mov_b32 m0, s20
	s_nop 0
	global_load_lds_dwordx4 v132, s[18:19]
	s_add_i32 m0, s20, 0x2000
	s_nop 0
	global_load_lds_dwordx4 v136, s[18:19]
	s_waitcnt vmcnt(6)
	s_barrier
	v_mfma_f32_16x16x32_bf16 v[46:49], v[204:207], v[162:165], v[46:49]
	v_mfma_f32_16x16x32_bf16 v[42:45], v[212:215], v[162:165], v[42:45]
	v_mfma_f32_16x16x32_bf16 v[30:33], v[204:207], v[170:173], v[30:33]
	v_mfma_f32_16x16x32_bf16 v[26:29], v[212:215], v[170:173], v[26:29]
	v_mfma_f32_16x16x32_bf16 v[14:17], v[204:207], v[178:181], v[14:17]
	v_mfma_f32_16x16x32_bf16 v[10:13], v[212:215], v[178:181], v[10:13]
	v_mfma_f32_16x16x32_bf16 v[6:9], v[204:207], v[196:199], v[6:9]
	v_mfma_f32_16x16x32_bf16 v[2:5], v[212:215], v[196:199], v[2:5]
	v_mfma_f32_16x16x32_bf16 v[46:49], v[208:211], v[166:169], v[46:49]
	v_mfma_f32_16x16x32_bf16 v[42:45], v[216:219], v[166:169], v[42:45]
	v_mfma_f32_16x16x32_bf16 v[30:33], v[208:211], v[174:177], v[30:33]
	v_mfma_f32_16x16x32_bf16 v[26:29], v[216:219], v[174:177], v[26:29]
	v_mfma_f32_16x16x32_bf16 v[14:17], v[208:211], v[182:185], v[14:17]
	v_mfma_f32_16x16x32_bf16 v[10:13], v[216:219], v[182:185], v[10:13]
	v_mfma_f32_16x16x32_bf16 v[6:9], v[208:211], v[200:203], v[6:9]
	v_mfma_f32_16x16x32_bf16 v[2:5], v[216:219], v[200:203], v[2:5]
	s_add_i32 s56, s56, 2
	s_add_u32 s53, s53, 0x100
	s_addc_u32 s55, s55, 0
	s_add_u32 s16, s16, 0x100
	s_addc_u32 s17, s17, 0
	s_cmp_gt_u32 s56, 29
	s_barrier
	s_cbranch_scc0 .LBB0_202
; __device__ __forceinline__ unsigned cvt_pk_bf16(float lo, float hi) { f32x2_t f = {lo, hi}; bf16x2_t v = __builtin_convertvector(f, bf16x2_t); return __builtin_bit_cast(unsigned, v); }
;     __device__ __forceinline__ void operator()(const f32x4 (&acc)[2][2][4][2], const Unit& u, int wr, int wc, int fr, int fq) const {
;         const int row0 = u.pm * BM + wr * 64 + fr; int colt = u.pn * BM; bf16_t* base = O;
;         if (split_cols) { const int t = colt / split_cols; base += (size_t)t * split_stride; colt -= t * split_cols; }
;         const int col0 = colt + wc * 32 + 8 * fq;
; #pragma unroll
;         for (int ai = 0; ai < 2; ++ai)
; #pragma unroll
;             for (int m = 0; m < 4; ++m) { bf16_t* rowp = base + (size_t)(row0 + ai * HALF + m * 16) * ldc + col0;
; #pragma unroll
;                 for (int bj = 0; bj < 2; ++bj) { const f32x4 v0 = acc[ai][bj][m][0], v1 = acc[ai][bj][m][1];
;                     u32x4 w; w.x = cvt_pk_bf16(v0[0], v0[1]); w.y = cvt_pk_bf16(v0[2], v0[3]); w.z = cvt_pk_bf16(v1[0], v1[1]); w.w = cvt_pk_bf16(v1[2], v1[3]);
;                     *(u32x4*)(rowp + bj * HALF) = w; } }
	v_lshl_add_u32 v146, s6, 8, v1
	v_lshl_or_b32 v148, s46, 8, v143
	v_ashrrev_i32_e32 v149, 31, v148
	v_ashrrev_i32_e32 v147, 31, v146
	v_lshl_add_u64 v[148:149], v[148:149], 1, s[4:5]
	v_lshlrev_b64 v[150:151], 14, v[146:147]
	v_lshl_add_u64 v[150:151], v[148:149], 0, v[150:151]
	s_mov_b32 s6, 0x200000
	s_mov_b64 s[16:17], 0x200000
	v_cvt_pk_bf16_f32 v62, v62, v63
	v_cvt_pk_bf16_f32 v63, v64, v65
	v_cvt_pk_bf16_f32 v64, v58, v59
	v_add_co_u32_e32 v58, vcc, s6, v150
	v_cvt_pk_bf16_f32 v70, v70, v71
	v_cvt_pk_bf16_f32 v71, v72, v73
	v_cvt_pk_bf16_f32 v72, v66, v67
	v_lshl_add_u64 v[66:67], v[150:151], 0, s[16:17]
	v_addc_co_u32_e32 v59, vcc, 0, v151, vcc
	v_cvt_pk_bf16_f32 v46, v46, v47
	v_cvt_pk_bf16_f32 v47, v48, v49
	v_cvt_pk_bf16_f32 v48, v42, v43
	v_cvt_pk_bf16_f32 v49, v44, v45
	s_mov_b32 s6, 0x240000
	global_store_dwordx4 v[66:67], v[46:49], off offset:256
	s_mov_b64 s[16:17], 0x240000
	v_cvt_pk_bf16_f32 v110, v110, v111
	v_add_co_u32_e32 v48, vcc, s6, v150
	v_cvt_pk_bf16_f32 v111, v112, v113
	v_cvt_pk_bf16_f32 v112, v106, v107
	v_or_b32_e32 v106, 16, v146
	v_lshl_add_u64 v[46:47], v[150:151], 0, s[16:17]
	v_addc_co_u32_e32 v49, vcc, 0, v151, vcc
	v_cvt_pk_bf16_f32 v30, v30, v31
	v_cvt_pk_bf16_f32 v31, v32, v33
	v_cvt_pk_bf16_f32 v32, v26, v27
	v_cvt_pk_bf16_f32 v33, v28, v29
	s_mov_b32 s6, 0x280000
	v_ashrrev_i32_e32 v107, 31, v106
	v_cvt_pk_bf16_f32 v94, v94, v95
	v_cvt_pk_bf16_f32 v95, v96, v97
	v_cvt_pk_bf16_f32 v96, v90, v91
	v_or_b32_e32 v90, 32, v146
	global_store_dwordx4 v[46:47], v[30:33], off offset:256
	s_mov_b64 s[16:17], 0x280000
	v_cvt_pk_bf16_f32 v113, v108, v109
	v_add_co_u32_e32 v32, vcc, s6, v150
	v_lshlrev_b64 v[106:107], 14, v[106:107]
	v_ashrrev_i32_e32 v91, 31, v90
	v_cvt_pk_bf16_f32 v78, v78, v79
	v_cvt_pk_bf16_f32 v79, v80, v81
	v_cvt_pk_bf16_f32 v80, v74, v75
	v_or_b32_e32 v74, 48, v146
	v_lshl_add_u64 v[30:31], v[150:151], 0, s[16:17]
	v_addc_co_u32_e32 v33, vcc, 0, v151, vcc
	v_cvt_pk_bf16_f32 v14, v14, v15
	v_cvt_pk_bf16_f32 v15, v16, v17
	v_cvt_pk_bf16_f32 v16, v10, v11
	v_cvt_pk_bf16_f32 v17, v12, v13
	global_store_dwordx4 v[150:151], v[110:113], off offset:256
	v_cvt_pk_bf16_f32 v97, v92, v93
	v_lshlrev_b64 v[90:91], 14, v[90:91]
	v_lshl_add_u64 v[110:111], v[148:149], 0, v[106:107]
	v_ashrrev_i32_e32 v75, 31, v74
	global_store_dwordx4 v[30:31], v[14:17], off offset:256
	global_store_dwordx4 v[110:111], v[94:97], off offset:256
	v_cvt_pk_bf16_f32 v81, v76, v77
	v_add_co_u32_e32 v16, vcc, s33, v150
	v_lshl_add_u64 v[94:95], v[148:149], 0, v[90:91]
	v_lshlrev_b64 v[74:75], 14, v[74:75]
	s_mov_b64 s[16:17], 0x2c0000
	v_addc_co_u32_e32 v17, vcc, 0, v151, vcc
	v_cvt_pk_bf16_f32 v126, v126, v127
	v_cvt_pk_bf16_f32 v127, v128, v129
	v_cvt_pk_bf16_f32 v128, v122, v123
	v_cvt_pk_bf16_f32 v129, v124, v125
	v_cvt_pk_bf16_f32 v106, v118, v119
	v_cvt_pk_bf16_f32 v107, v120, v121
	v_cvt_pk_bf16_f32 v108, v114, v115
	v_cvt_pk_bf16_f32 v109, v116, v117
	v_cvt_pk_bf16_f32 v90, v102, v103
	v_cvt_pk_bf16_f32 v91, v104, v105
	v_cvt_pk_bf16_f32 v92, v98, v99
	v_cvt_pk_bf16_f32 v93, v100, v101
	global_store_dwordx4 v[94:95], v[78:81], off offset:256
	v_cvt_pk_bf16_f32 v76, v82, v83
	v_cvt_pk_bf16_f32 v77, v84, v85
	v_lshl_add_u64 v[78:79], v[148:149], 0, v[74:75]
	v_cvt_pk_bf16_f32 v74, v86, v87
	v_cvt_pk_bf16_f32 v75, v88, v89
	v_cvt_pk_bf16_f32 v73, v68, v69
	v_cvt_pk_bf16_f32 v65, v60, v61
	v_cvt_pk_bf16_f32 v42, v54, v55
	v_cvt_pk_bf16_f32 v43, v56, v57
	v_cvt_pk_bf16_f32 v44, v50, v51
	v_cvt_pk_bf16_f32 v45, v52, v53
	v_cvt_pk_bf16_f32 v26, v38, v39
	v_cvt_pk_bf16_f32 v27, v40, v41
	v_cvt_pk_bf16_f32 v28, v34, v35
	v_cvt_pk_bf16_f32 v29, v36, v37
	v_lshl_add_u64 v[14:15], v[150:151], 0, s[16:17]
	v_cvt_pk_bf16_f32 v10, v22, v23
	v_cvt_pk_bf16_f32 v11, v24, v25
	v_cvt_pk_bf16_f32 v12, v18, v19
	v_cvt_pk_bf16_f32 v13, v20, v21
	v_cvt_pk_bf16_f32 v6, v6, v7
	v_cvt_pk_bf16_f32 v7, v8, v9
	v_cvt_pk_bf16_f32 v8, v2, v3
	v_cvt_pk_bf16_f32 v9, v4, v5
	s_and_b64 vcc, exec, s[0:1]
	s_mov_b32 s46, s8
	s_mov_b32 s6, s10
	s_mov_b64 s[16:17], s[14:15]
	s_mov_b64 s[18:19], s[12:13]
	s_mov_b32 s39, 0xb2a5705f
	s_mov_b32 s38, 0x42ce8ed0
	s_mov_b64 s[52:53], 0x41000
	global_store_dwordx4 v[150:151], v[126:129], off
	global_store_dwordx4 v[110:111], v[106:109], off
	global_store_dwordx4 v[94:95], v[90:93], off
	global_store_dwordx4 v[78:79], v[74:77], off
	global_store_dwordx4 v[78:79], v[70:73], off offset:256
	global_store_dwordx4 v[58:59], v[62:65], off
	global_store_dwordx4 v[48:49], v[42:45], off
	global_store_dwordx4 v[32:33], v[26:29], off
	global_store_dwordx4 v[16:17], v[10:13], off
	global_store_dwordx4 v[14:15], v[6:9], off offset:256
	s_cbranch_vccz .LBB0_195
	s_waitcnt vmcnt(0)
	s_cmpk_gt_u32 s25, 0xff
	s_cbranch_scc1 .LBB0_206
	s_barrier

; #define PG8_STAGE(bufoff, gbase, voff) do { _Pragma("unroll") for (int _i = 0; _i < 2; ++_i) \
;         __builtin_amdgcn_global_load_lds((const unsigned*)((const char*)(gbase) + (voff)[_i]), (LAS unsigned*)(lds + (bufoff) + ldsw + _i * 8192), 16, 0, 0); } while (0)
; #define PG8_LDA(dst, b, h) do { _Pragma("unroll") for (int m = 0; m < 4; ++m) _Pragma("unroll") for (int k = 0; k < 2; ++k) dst[m][k] = *(const LAS bf16x8*)(lds + PG8_SA(b, h) + aoff + m * 2048 + k * 1024); } while (0)
; #define PG8_LDB(dst, b, h) do { _Pragma("unroll") for (int n = 0; n < 2; ++n) _Pragma("unroll") for (int k = 0; k < 2; ++k) dst[n][k] = *(const LAS bf16x8*)(lds + PG8_SB(b, h) + boff + n * 2048 + k * 1024); } while (0)
; #define PG8_MMA(ai, bj, At, Bt) do { __builtin_amdgcn_s_setprio(1); _Pragma("unroll") for (int m = 0; m < 4; ++m) _Pragma("unroll") for (int n = 0; n < 2; ++n) _Pragma("unroll") for (int k = 0; k < 2; ++k) \
;         acc[ai][bj][m][n] = __builtin_amdgcn_mfma_f32_16x16x32_bf16(Bt[n][k], At[m][k], acc[ai][bj][m][n], 0, 0, 0); __builtin_amdgcn_s_setprio(0); } while (0)
; #define PG8_WAIT_V(n) asm volatile("s_waitcnt vmcnt(" #n ")" ::: "memory")
; #define PG8_WAIT_L(n) asm volatile("s_waitcnt lgkmcnt(" #n ")" ::: "memory")
; #define PG8_BAR __builtin_amdgcn_s_barrier()
; #define PG8_SCHED __builtin_amdgcn_sched_barrier(0)
; template <class Epi, class Sched, bool AREMAP>
; __device__ __forceinline__ void gemm_phase(LAS unsigned char* lds, const Gemm g, const Sched& S, const Epi& E, int wv) {
;     ...
;             PG8_LDB(B0, 0, 0); PG8_SCHED; PG8_LDA(At, 0, 0); PG8_STAGE(PG8_SA(1, 1), a1 + hstepA, voffA);
;             PG8_WAIT_L(8); PG8_BAR; PG8_WAIT_L(0); PG8_MMA(0, 0, At, B0); PG8_BAR; PG8_SCHED;
;             PG8_LDB(B1, 0, 1); PG8_STAGE(PG8_SB(0, 0), b2, voffB);
;             PG8_BAR; PG8_WAIT_L(0); PG8_MMA(0, 1, At, B1); PG8_BAR;
;             PG8_LDA(At, 0, 1); PG8_STAGE(PG8_SA(0, 0), a2, voffA);
;             PG8_BAR; PG8_WAIT_L(0); PG8_MMA(1, 0, At, B0); PG8_BAR; PG8_SCHED;
;             PG8_STAGE(PG8_SB(0, 1), b2 + hstepB, voffB);
;             PG8_WAIT_V(6); PG8_BAR; PG8_MMA(1, 1, At, B1); PG8_BAR;
.LBB0_397:
	s_add_u32 s14, s2, 0xfffc0080
	s_addc_u32 s15, s3, -1
	s_add_i32 s38, 0, 0x10000
	v_add_u32_e32 v145, s38, v142
	ds_read_b128 v[146:149], v145
	ds_read_b128 v[150:153], v145 offset:1024
	ds_read_b128 v[154:157], v145 offset:2048
	ds_read_b128 v[158:161], v145 offset:3072
	s_cmp_eq_u32 s53, 12
	s_cselect_b32 s17, s11, s15
	s_cselect_b32 s16, s10, s14
	s_cselect_b32 s15, s7, s52
	s_cselect_b32 s14, s9, s47
	s_add_i32 m0, s5, 0xc000
	ds_read_b128 v[162:165], v144
	ds_read_b128 v[166:169], v144 offset:1024
	ds_read_b128 v[170:173], v144 offset:2048
	ds_read_b128 v[174:177], v144 offset:3072
	ds_read_b128 v[178:181], v144 offset:4096
	ds_read_b128 v[182:185], v144 offset:5120
	ds_read_b128 v[192:195], v144 offset:6144
	ds_read_b128 v[196:199], v144 offset:7168
	global_load_lds_dwordx4 v140, s[2:3]
	s_add_i32 m0, s5, 0xe000
	s_nop 0
	global_load_lds_dwordx4 v138, s[2:3]
	s_waitcnt lgkmcnt(8)
	s_barrier
	s_waitcnt lgkmcnt(0)
	s_waitcnt lgkmcnt(0)
	v_mfma_f32_16x16x32_bf16 v[126:129], v[146:149], v[162:165], v[126:129]
	v_mfma_f32_16x16x32_bf16 v[122:125], v[154:157], v[162:165], v[122:125]
	v_mfma_f32_16x16x32_bf16 v[118:121], v[146:149], v[170:173], v[118:121]
	v_mfma_f32_16x16x32_bf16 v[114:117], v[154:157], v[170:173], v[114:117]
	v_mfma_f32_16x16x32_bf16 v[102:105], v[146:149], v[178:181], v[102:105]
	v_mfma_f32_16x16x32_bf16 v[98:101], v[154:157], v[178:181], v[98:101]
	v_mfma_f32_16x16x32_bf16 v[86:89], v[146:149], v[192:195], v[86:89]
	v_mfma_f32_16x16x32_bf16 v[82:85], v[154:157], v[192:195], v[82:85]
	v_mfma_f32_16x16x32_bf16 v[126:129], v[150:153], v[166:169], v[126:129]
	v_mfma_f32_16x16x32_bf16 v[122:125], v[158:161], v[166:169], v[122:125]
	v_mfma_f32_16x16x32_bf16 v[118:121], v[150:153], v[174:177], v[118:121]
	v_mfma_f32_16x16x32_bf16 v[114:117], v[158:161], v[174:177], v[114:117]
	v_mfma_f32_16x16x32_bf16 v[102:105], v[150:153], v[182:185], v[102:105]
	v_mfma_f32_16x16x32_bf16 v[98:101], v[158:161], v[182:185], v[98:101]
	v_mfma_f32_16x16x32_bf16 v[86:89], v[150:153], v[196:199], v[86:89]
	v_mfma_f32_16x16x32_bf16 v[82:85], v[158:161], v[196:199], v[82:85]
	s_barrier
	s_add_i32 s39, 0, 0x14000
	s_add_i32 s38, s38, s26
	v_add_u32_e32 v145, s39, v142
	s_add_u32 s80, s14, 0x80
	s_addc_u32 s81, s15, 0
	s_mov_b32 m0, s38
	ds_read_b128 v[200:203], v145
	ds_read_b128 v[204:207], v145 offset:1024
	ds_read_b128 v[208:211], v145 offset:2048
	ds_read_b128 v[212:215], v145 offset:3072
	global_load_lds_dwordx4 v134, s[14:15]
	s_add_i32 m0, s38, 0x2000
	s_nop 0
	global_load_lds_dwordx4 v130, s[14:15]
	s_barrier
	s_waitcnt lgkmcnt(0)
	s_waitcnt lgkmcnt(0)
	v_mfma_f32_16x16x32_bf16 v[110:113], v[200:203], v[162:165], v[110:113]
	v_mfma_f32_16x16x32_bf16 v[106:109], v[208:211], v[162:165], v[106:109]
	v_mfma_f32_16x16x32_bf16 v[94:97], v[200:203], v[170:173], v[94:97]
	v_mfma_f32_16x16x32_bf16 v[90:93], v[208:211], v[170:173], v[90:93]
	v_mfma_f32_16x16x32_bf16 v[78:81], v[200:203], v[178:181], v[78:81]
	v_mfma_f32_16x16x32_bf16 v[74:77], v[208:211], v[178:181], v[74:77]
	v_mfma_f32_16x16x32_bf16 v[70:73], v[200:203], v[192:195], v[70:73]
	v_mfma_f32_16x16x32_bf16 v[66:69], v[208:211], v[192:195], v[66:69]
	v_mfma_f32_16x16x32_bf16 v[110:113], v[204:207], v[166:169], v[110:113]
	v_mfma_f32_16x16x32_bf16 v[106:109], v[212:215], v[166:169], v[106:109]
	v_mfma_f32_16x16x32_bf16 v[94:97], v[204:207], v[174:177], v[94:97]
	v_mfma_f32_16x16x32_bf16 v[90:93], v[212:215], v[174:177], v[90:93]
	v_mfma_f32_16x16x32_bf16 v[78:81], v[204:207], v[182:185], v[78:81]
	v_mfma_f32_16x16x32_bf16 v[74:77], v[212:215], v[182:185], v[74:77]
	v_mfma_f32_16x16x32_bf16 v[70:73], v[204:207], v[196:199], v[70:73]
	v_mfma_f32_16x16x32_bf16 v[66:69], v[212:215], v[196:199], v[66:69]
	s_mov_b32 m0, s5
	s_add_u32 s96, s16, 0x80
	s_addc_u32 s97, s17, 0
	s_barrier
	ds_read_b128 v[162:165], v144 offset:16384
	ds_read_b128 v[166:169], v144 offset:17408
	ds_read_b128 v[170:173], v144 offset:18432
	ds_read_b128 v[174:177], v144 offset:19456
	ds_read_b128 v[178:181], v144 offset:20480
	ds_read_b128 v[182:185], v144 offset:21504
	ds_read_b128 v[192:195], v144 offset:22528
	ds_read_b128 v[196:199], v144 offset:23552
	global_load_lds_dwordx4 v136, s[16:17]
	s_mov_b32 m0, s28
	s_nop 0
	global_load_lds_dwordx4 v132, s[16:17]
	s_barrier
	s_waitcnt lgkmcnt(0)
	s_waitcnt lgkmcnt(0)
	v_mfma_f32_16x16x32_bf16 v[62:65], v[146:149], v[162:165], v[62:65]
	v_mfma_f32_16x16x32_bf16 v[58:61], v[154:157], v[162:165], v[58:61]
	v_mfma_f32_16x16x32_bf16 v[54:57], v[146:149], v[170:173], v[54:57]
	v_mfma_f32_16x16x32_bf16 v[50:53], v[154:157], v[170:173], v[50:53]
	v_mfma_f32_16x16x32_bf16 v[38:41], v[146:149], v[178:181], v[38:41]
	v_mfma_f32_16x16x32_bf16 v[34:37], v[154:157], v[178:181], v[34:37]
	v_mfma_f32_16x16x32_bf16 v[22:25], v[146:149], v[192:195], v[22:25]
	v_mfma_f32_16x16x32_bf16 v[18:21], v[154:157], v[192:195], v[18:21]
	v_mfma_f32_16x16x32_bf16 v[62:65], v[150:153], v[166:169], v[62:65]
	v_mfma_f32_16x16x32_bf16 v[58:61], v[158:161], v[166:169], v[58:61]
	v_mfma_f32_16x16x32_bf16 v[54:57], v[150:153], v[174:177], v[54:57]
	v_mfma_f32_16x16x32_bf16 v[50:53], v[158:161], v[174:177], v[50:53]
	v_mfma_f32_16x16x32_bf16 v[38:41], v[150:153], v[182:185], v[38:41]
	v_mfma_f32_16x16x32_bf16 v[34:37], v[158:161], v[182:185], v[34:37]
	v_mfma_f32_16x16x32_bf16 v[22:25], v[150:153], v[196:199], v[22:25]
	v_mfma_f32_16x16x32_bf16 v[18:21], v[158:161], v[196:199], v[18:21]
	s_barrier
	s_add_u32 s56, s14, 0x40000
	s_addc_u32 s57, s15, 0
	s_add_i32 s38, s39, s26
	s_mov_b32 m0, s38
	s_nop 0
	global_load_lds_dwordx4 v134, s[56:57]
	s_add_i32 m0, s38, 0x2000
	s_nop 0
	global_load_lds_dwordx4 v130, s[56:57]
	s_waitcnt vmcnt(6)
	s_barrier
; #define PG8_STAGE(bufoff, gbase, voff) do { _Pragma("unroll") for (int _i = 0; _i < 2; ++_i) \
;         __builtin_amdgcn_global_load_lds((const unsigned*)((const char*)(gbase) + (voff)[_i]), (LAS unsigned*)(lds + (bufoff) + ldsw + _i * 8192), 16, 0, 0); } while (0)
; #define PG8_LDA(dst, b, h) do { _Pragma("unroll") for (int m = 0; m < 4; ++m) _Pragma("unroll") for (int k = 0; k < 2; ++k) dst[m][k] = *(const LAS bf16x8*)(lds + PG8_SA(b, h) + aoff + m * 2048 + k * 1024); } while (0)
; #define PG8_LDB(dst, b, h) do { _Pragma("unroll") for (int n = 0; n < 2; ++n) _Pragma("unroll") for (int k = 0; k < 2; ++k) dst[n][k] = *(const LAS bf16x8*)(lds + PG8_SB(b, h) + boff + n * 2048 + k * 1024); } while (0)
; #define PG8_MMA(ai, bj, At, Bt) do { __builtin_amdgcn_s_setprio(1); _Pragma("unroll") for (int m = 0; m < 4; ++m) _Pragma("unroll") for (int n = 0; n < 2; ++n) _Pragma("unroll") for (int k = 0; k < 2; ++k) \
;         acc[ai][bj][m][n] = __builtin_amdgcn_mfma_f32_16x16x32_bf16(Bt[n][k], At[m][k], acc[ai][bj][m][n], 0, 0, 0); __builtin_amdgcn_s_setprio(0); } while (0)
; #define PG8_WAIT_V(n) asm volatile("s_waitcnt vmcnt(" #n ")" ::: "memory")
; #define PG8_WAIT_L(n) asm volatile("s_waitcnt lgkmcnt(" #n ")" ::: "memory")
; #define PG8_BAR __builtin_amdgcn_s_barrier()
; #define PG8_SCHED __builtin_amdgcn_sched_barrier(0)
; template <class Epi, class Sched, bool AREMAP>
; __device__ __forceinline__ void gemm_phase(LAS unsigned char* lds, const Gemm g, const Sched& S, const Epi& E, int wv) {
;     ...
;             PG8_WAIT_V(6); PG8_BAR; PG8_MMA(1, 1, At, B1); PG8_BAR;
;             PG8_LDB(B0, 1, 0); PG8_SCHED; PG8_LDA(At, 1, 0); PG8_STAGE(PG8_SA(0, 1), a2 + hstepA, voffA);
;             PG8_WAIT_L(8); PG8_BAR; PG8_WAIT_L(0); PG8_MMA(0, 0, At, B0); PG8_BAR; PG8_SCHED;
;             PG8_LDB(B1, 1, 1); PG8_STAGE(PG8_SB(1, 0), b3, voffB);
;             PG8_BAR; PG8_WAIT_L(0); PG8_MMA(0, 1, At, B1); PG8_BAR;
;             PG8_LDA(At, 1, 1); PG8_STAGE(PG8_SA(1, 0), a3, voffA);
	v_mfma_f32_16x16x32_bf16 v[46:49], v[200:203], v[162:165], v[46:49]
	v_mfma_f32_16x16x32_bf16 v[42:45], v[208:211], v[162:165], v[42:45]
	v_mfma_f32_16x16x32_bf16 v[30:33], v[200:203], v[170:173], v[30:33]
	v_mfma_f32_16x16x32_bf16 v[26:29], v[208:211], v[170:173], v[26:29]
	v_mfma_f32_16x16x32_bf16 v[14:17], v[200:203], v[178:181], v[14:17]
	v_mfma_f32_16x16x32_bf16 v[10:13], v[208:211], v[178:181], v[10:13]
	v_mfma_f32_16x16x32_bf16 v[6:9], v[200:203], v[192:195], v[6:9]
	v_mfma_f32_16x16x32_bf16 v[2:5], v[208:211], v[192:195], v[2:5]
	v_mfma_f32_16x16x32_bf16 v[46:49], v[204:207], v[166:169], v[46:49]
	v_mfma_f32_16x16x32_bf16 v[42:45], v[212:215], v[166:169], v[42:45]
	v_mfma_f32_16x16x32_bf16 v[30:33], v[204:207], v[174:177], v[30:33]
	v_mfma_f32_16x16x32_bf16 v[26:29], v[212:215], v[174:177], v[26:29]
	v_mfma_f32_16x16x32_bf16 v[14:17], v[204:207], v[182:185], v[14:17]
	v_mfma_f32_16x16x32_bf16 v[10:13], v[212:215], v[182:185], v[10:13]
	v_mfma_f32_16x16x32_bf16 v[6:9], v[204:207], v[196:199], v[6:9]
	v_mfma_f32_16x16x32_bf16 v[2:5], v[212:215], v[196:199], v[2:5]
	s_add_i32 s38, 0, 0x18000
	v_add_u32_e32 v145, s38, v142
	s_barrier
	ds_read_b128 v[146:149], v145
	ds_read_b128 v[150:153], v145 offset:1024
	ds_read_b128 v[154:157], v145 offset:2048
	ds_read_b128 v[158:161], v145 offset:3072
	s_add_u32 s16, s16, 0x40000
	s_addc_u32 s17, s17, 0
	s_mov_b32 m0, s29
	ds_read_b128 v[162:165], v144 offset:32768
	ds_read_b128 v[166:169], v144 offset:33792
	ds_read_b128 v[170:173], v144 offset:34816
	ds_read_b128 v[174:177], v144 offset:35840
	ds_read_b128 v[178:181], v144 offset:36864
	ds_read_b128 v[182:185], v144 offset:37888
	ds_read_b128 v[192:195], v144 offset:38912
	ds_read_b128 v[196:199], v144 offset:39936
	global_load_lds_dwordx4 v136, s[16:17]
	s_mov_b32 m0, s30
	s_nop 0
	global_load_lds_dwordx4 v132, s[16:17]
	s_waitcnt lgkmcnt(8)
	s_barrier
	s_waitcnt lgkmcnt(0)
	s_waitcnt lgkmcnt(0)
	v_mfma_f32_16x16x32_bf16 v[126:129], v[146:149], v[162:165], v[126:129]
	v_mfma_f32_16x16x32_bf16 v[122:125], v[154:157], v[162:165], v[122:125]
	v_mfma_f32_16x16x32_bf16 v[118:121], v[146:149], v[170:173], v[118:121]
	v_mfma_f32_16x16x32_bf16 v[114:117], v[154:157], v[170:173], v[114:117]
	v_mfma_f32_16x16x32_bf16 v[102:105], v[146:149], v[178:181], v[102:105]
	v_mfma_f32_16x16x32_bf16 v[98:101], v[154:157], v[178:181], v[98:101]
	v_mfma_f32_16x16x32_bf16 v[86:89], v[146:149], v[192:195], v[86:89]
	v_mfma_f32_16x16x32_bf16 v[82:85], v[154:157], v[192:195], v[82:85]
	v_mfma_f32_16x16x32_bf16 v[126:129], v[150:153], v[166:169], v[126:129]
	v_mfma_f32_16x16x32_bf16 v[122:125], v[158:161], v[166:169], v[122:125]
	v_mfma_f32_16x16x32_bf16 v[118:121], v[150:153], v[174:177], v[118:121]
	v_mfma_f32_16x16x32_bf16 v[114:117], v[158:161], v[174:177], v[114:117]
	v_mfma_f32_16x16x32_bf16 v[102:105], v[150:153], v[182:185], v[102:105]
	v_mfma_f32_16x16x32_bf16 v[98:101], v[158:161], v[182:185], v[98:101]
	v_mfma_f32_16x16x32_bf16 v[86:89], v[150:153], v[196:199], v[86:89]
	v_mfma_f32_16x16x32_bf16 v[82:85], v[158:161], v[196:199], v[82:85]
	s_barrier
	s_add_i32 s16, 0, 0x1c000
	s_add_i32 s17, s38, s26
	v_add_u32_e32 v145, s16, v142
	s_mov_b32 m0, s17
	ds_read_b128 v[200:203], v145
	ds_read_b128 v[204:207], v145 offset:1024
	ds_read_b128 v[208:211], v145 offset:2048
	ds_read_b128 v[212:215], v145 offset:3072
	global_load_lds_dwordx4 v134, s[80:81]
	s_add_i32 m0, s17, 0x2000
	s_nop 0
	global_load_lds_dwordx4 v130, s[80:81]
	s_barrier
	s_waitcnt lgkmcnt(0)
	s_waitcnt lgkmcnt(0)
	v_mfma_f32_16x16x32_bf16 v[110:113], v[200:203], v[162:165], v[110:113]
	v_mfma_f32_16x16x32_bf16 v[106:109], v[208:211], v[162:165], v[106:109]
	v_mfma_f32_16x16x32_bf16 v[94:97], v[200:203], v[170:173], v[94:97]
	v_mfma_f32_16x16x32_bf16 v[90:93], v[208:211], v[170:173], v[90:93]
	v_mfma_f32_16x16x32_bf16 v[78:81], v[200:203], v[178:181], v[78:81]
	v_mfma_f32_16x16x32_bf16 v[74:77], v[208:211], v[178:181], v[74:77]
	v_mfma_f32_16x16x32_bf16 v[70:73], v[200:203], v[192:195], v[70:73]
	v_mfma_f32_16x16x32_bf16 v[66:69], v[208:211], v[192:195], v[66:69]
	v_mfma_f32_16x16x32_bf16 v[110:113], v[204:207], v[166:169], v[110:113]
	v_mfma_f32_16x16x32_bf16 v[106:109], v[212:215], v[166:169], v[106:109]
	v_mfma_f32_16x16x32_bf16 v[94:97], v[204:207], v[174:177], v[94:97]
	v_mfma_f32_16x16x32_bf16 v[90:93], v[212:215], v[174:177], v[90:93]
	v_mfma_f32_16x16x32_bf16 v[78:81], v[204:207], v[182:185], v[78:81]
	v_mfma_f32_16x16x32_bf16 v[74:77], v[212:215], v[182:185], v[74:77]
	v_mfma_f32_16x16x32_bf16 v[70:73], v[204:207], v[196:199], v[70:73]
	v_mfma_f32_16x16x32_bf16 v[66:69], v[212:215], v[196:199], v[66:69]
	s_mov_b32 m0, s35
	s_barrier
	ds_read_b128 v[162:165], v144 offset:49152
	ds_read_b128 v[166:169], v144 offset:50176
	ds_read_b128 v[170:173], v144 offset:51200
	ds_read_b128 v[174:177], v144 offset:52224
	ds_read_b128 v[178:181], v144 offset:53248
	ds_read_b128 v[182:185], v144 offset:54272
	ds_read_b128 v[192:195], v144 offset:55296
	ds_read_b128 v[196:199], v144 offset:56320
	global_load_lds_dwordx4 v136, s[96:97]
	s_mov_b32 m0, s36
	s_nop 0
	global_load_lds_dwordx4 v132, s[96:97]
	s_barrier
; #define PG8_STAGE(bufoff, gbase, voff) do { _Pragma("unroll") for (int _i = 0; _i < 2; ++_i) \
;         __builtin_amdgcn_global_load_lds((const unsigned*)((const char*)(gbase) + (voff)[_i]), (LAS unsigned*)(lds + (bufoff) + ldsw + _i * 8192), 16, 0, 0); } while (0)
; #define PG8_MMA(ai, bj, At, Bt) do { __builtin_amdgcn_s_setprio(1); _Pragma("unroll") for (int m = 0; m < 4; ++m) _Pragma("unroll") for (int n = 0; n < 2; ++n) _Pragma("unroll") for (int k = 0; k < 2; ++k) \
;         acc[ai][bj][m][n] = __builtin_amdgcn_mfma_f32_16x16x32_bf16(Bt[n][k], At[m][k], acc[ai][bj][m][n], 0, 0, 0); __builtin_amdgcn_s_setprio(0); } while (0)
; #define PG8_WAIT_V(n) asm volatile("s_waitcnt vmcnt(" #n ")" ::: "memory")
; #define PG8_WAIT_L(n) asm volatile("s_waitcnt lgkmcnt(" #n ")" ::: "memory")
; #define PG8_BAR __builtin_amdgcn_s_barrier()
; #define PG8_SCHED __builtin_amdgcn_sched_barrier(0)
; template <class Epi, class Sched, bool AREMAP>
; __device__ __forceinline__ void gemm_phase(LAS unsigned char* lds, const Gemm g, const Sched& S, const Epi& E, int wv) {
;     ...
;             PG8_BAR; PG8_WAIT_L(0); PG8_MMA(1, 0, At, B0); PG8_BAR; PG8_SCHED;
;             PG8_STAGE(PG8_SB(1, 1), b3 + hstepB, voffB);
;             PG8_WAIT_V(6); PG8_BAR; PG8_MMA(1, 1, At, B1); PG8_BAR;
	s_waitcnt lgkmcnt(0)
	s_waitcnt lgkmcnt(0)
	v_mfma_f32_16x16x32_bf16 v[62:65], v[146:149], v[162:165], v[62:65]
	v_mfma_f32_16x16x32_bf16 v[58:61], v[154:157], v[162:165], v[58:61]
	v_mfma_f32_16x16x32_bf16 v[54:57], v[146:149], v[170:173], v[54:57]
	v_mfma_f32_16x16x32_bf16 v[50:53], v[154:157], v[170:173], v[50:53]
	v_mfma_f32_16x16x32_bf16 v[38:41], v[146:149], v[178:181], v[38:41]
	v_mfma_f32_16x16x32_bf16 v[34:37], v[154:157], v[178:181], v[34:37]
	v_mfma_f32_16x16x32_bf16 v[22:25], v[146:149], v[192:195], v[22:25]
	v_mfma_f32_16x16x32_bf16 v[18:21], v[154:157], v[192:195], v[18:21]
	v_mfma_f32_16x16x32_bf16 v[62:65], v[150:153], v[166:169], v[62:65]
	v_mfma_f32_16x16x32_bf16 v[58:61], v[158:161], v[166:169], v[58:61]
	v_mfma_f32_16x16x32_bf16 v[54:57], v[150:153], v[174:177], v[54:57]
	v_mfma_f32_16x16x32_bf16 v[50:53], v[158:161], v[174:177], v[50:53]
	v_mfma_f32_16x16x32_bf16 v[38:41], v[150:153], v[182:185], v[38:41]
	v_mfma_f32_16x16x32_bf16 v[34:37], v[158:161], v[182:185], v[34:37]
	v_mfma_f32_16x16x32_bf16 v[22:25], v[150:153], v[196:199], v[22:25]
	v_mfma_f32_16x16x32_bf16 v[18:21], v[158:161], v[196:199], v[18:21]
	s_barrier
	s_add_u32 s14, s14, 0x40080
	s_addc_u32 s15, s15, 0
	s_add_i32 s16, s16, s26
	s_mov_b32 m0, s16
	s_nop 0
	global_load_lds_dwordx4 v134, s[14:15]
	s_add_i32 m0, s16, 0x2000
	s_nop 0
	global_load_lds_dwordx4 v130, s[14:15]
	s_waitcnt vmcnt(6)
	s_barrier
	v_mfma_f32_16x16x32_bf16 v[46:49], v[200:203], v[162:165], v[46:49]
	v_mfma_f32_16x16x32_bf16 v[42:45], v[208:211], v[162:165], v[42:45]
	v_mfma_f32_16x16x32_bf16 v[30:33], v[200:203], v[170:173], v[30:33]
	v_mfma_f32_16x16x32_bf16 v[26:29], v[208:211], v[170:173], v[26:29]
	v_mfma_f32_16x16x32_bf16 v[14:17], v[200:203], v[178:181], v[14:17]
	v_mfma_f32_16x16x32_bf16 v[10:13], v[208:211], v[178:181], v[10:13]
	v_mfma_f32_16x16x32_bf16 v[6:9], v[200:203], v[192:195], v[6:9]
	v_mfma_f32_16x16x32_bf16 v[2:5], v[208:211], v[192:195], v[2:5]
	v_mfma_f32_16x16x32_bf16 v[46:49], v[204:207], v[166:169], v[46:49]
	v_mfma_f32_16x16x32_bf16 v[42:45], v[212:215], v[166:169], v[42:45]
	v_mfma_f32_16x16x32_bf16 v[30:33], v[204:207], v[174:177], v[30:33]
	v_mfma_f32_16x16x32_bf16 v[26:29], v[212:215], v[174:177], v[26:29]
	v_mfma_f32_16x16x32_bf16 v[14:17], v[204:207], v[182:185], v[14:17]
	v_mfma_f32_16x16x32_bf16 v[10:13], v[212:215], v[182:185], v[10:13]
	v_mfma_f32_16x16x32_bf16 v[6:9], v[204:207], v[196:199], v[6:9]
	v_mfma_f32_16x16x32_bf16 v[2:5], v[212:215], v[196:199], v[2:5]
	s_add_i32 s53, s53, 2
	s_add_u32 s47, s47, 0x100
	s_addc_u32 s52, s52, 0
	s_add_u32 s2, s2, 0x100
	s_addc_u32 s3, s3, 0
	s_cmp_gt_u32 s53, 13
	s_barrier
	s_cbranch_scc0 .LBB0_397
; __device__ __forceinline__ unsigned cvt_pk_bf16(float lo, float hi) { f32x2_t f = {lo, hi}; bf16x2_t v = __builtin_convertvector(f, bf16x2_t); return __builtin_bit_cast(unsigned, v); }
;     __device__ __forceinline__ void operator()(const f32x4 (&acc)[2][2][4][2], const Unit& u, int wr, int wc, int fr, int fq) const {
;         const int row0 = u.pm * BM + wr * 64 + fr; int colt = u.pn * BM; bf16_t* base = O;
;         if (split_cols) { const int t = colt / split_cols; base += (size_t)t * split_stride; colt -= t * split_cols; }
;         const int col0 = colt + wc * 32 + 8 * fq;
; #pragma unroll
;         for (int ai = 0; ai < 2; ++ai)
; #pragma unroll
;             for (int m = 0; m < 4; ++m) { bf16_t* rowp = base + (size_t)(row0 + ai * HALF + m * 16) * ldc + col0;
; #pragma unroll
;                 for (int bj = 0; bj < 2; ++bj) { const f32x4 v0 = acc[ai][bj][m][0], v1 = acc[ai][bj][m][1];
;                     u32x4 w; w.x = cvt_pk_bf16(v0[0], v0[1]); w.y = cvt_pk_bf16(v0[2], v0[3]); w.z = cvt_pk_bf16(v1[0], v1[1]); w.w = cvt_pk_bf16(v1[2], v1[3]);
;                     *(u32x4*)(rowp + bj * HALF) = w; } }
	s_ashr_i32 s2, s46, 31
	s_lshr_b32 s2, s2, 29
	s_add_i32 s2, s46, s2
	s_ashr_i32 s2, s2, 3
	s_ashr_i32 s3, s2, 31
	s_lshl_b32 s7, s46, 8
	s_lshl_b64 s[14:15], s[2:3], 27
	s_add_u32 s14, s31, s14
	s_addc_u32 s15, s34, s15
	s_lshl_b32 s2, s2, 11
	s_sub_i32 s2, s7, s2
	v_lshl_add_u32 v146, s4, 8, v1
	v_or_b32_e32 v148, s2, v143
	v_ashrrev_i32_e32 v149, 31, v148
	v_ashrrev_i32_e32 v147, 31, v146
	v_lshl_add_u64 v[148:149], v[148:149], 1, s[14:15]
	v_lshlrev_b64 v[150:151], 12, v[146:147]
	v_lshl_add_u64 v[150:151], v[148:149], 0, v[150:151]
	s_mov_b64 s[2:3], 0x80000
	v_cvt_pk_bf16_f32 v70, v70, v71
	v_cvt_pk_bf16_f32 v71, v72, v73
	v_cvt_pk_bf16_f32 v72, v66, v67
	v_lshl_add_u64 v[66:67], v[150:151], 0, s[2:3]
	s_mov_b32 s2, 0x80000
	v_cvt_pk_bf16_f32 v62, v62, v63
	v_cvt_pk_bf16_f32 v63, v64, v65
	v_cvt_pk_bf16_f32 v64, v58, v59
	v_add_co_u32_e32 v58, vcc, s2, v150
	v_cvt_pk_bf16_f32 v46, v46, v47
	v_cvt_pk_bf16_f32 v47, v48, v49
	v_cvt_pk_bf16_f32 v48, v42, v43
	v_cvt_pk_bf16_f32 v49, v44, v45
	s_mov_b64 s[2:3], 0x90000
	v_addc_co_u32_e32 v59, vcc, 0, v151, vcc
	global_store_dwordx4 v[66:67], v[46:49], off offset:256
	v_cvt_pk_bf16_f32 v30, v30, v31
	v_cvt_pk_bf16_f32 v31, v32, v33
	v_lshl_add_u64 v[46:47], v[150:151], 0, s[2:3]
	s_mov_b32 s2, 0x90000
	v_add_co_u32_e32 v48, vcc, s2, v150
	v_cvt_pk_bf16_f32 v32, v26, v27
	v_cvt_pk_bf16_f32 v33, v28, v29
	s_mov_b64 s[2:3], 0xa0000
	v_cvt_pk_bf16_f32 v110, v110, v111
	v_cvt_pk_bf16_f32 v111, v112, v113
	v_cvt_pk_bf16_f32 v112, v106, v107
	v_or_b32_e32 v106, 16, v146
	v_addc_co_u32_e32 v49, vcc, 0, v151, vcc
	global_store_dwordx4 v[46:47], v[30:33], off offset:256
	v_ashrrev_i32_e32 v107, 31, v106
	v_cvt_pk_bf16_f32 v94, v94, v95
	v_lshl_add_u64 v[30:31], v[150:151], 0, s[2:3]
	s_mov_b32 s2, 0xa0000
	v_cvt_pk_bf16_f32 v95, v96, v97
	v_cvt_pk_bf16_f32 v96, v90, v91
	v_or_b32_e32 v90, 32, v146
	v_add_co_u32_e32 v32, vcc, s2, v150
	v_cvt_pk_bf16_f32 v14, v14, v15
	v_cvt_pk_bf16_f32 v15, v16, v17
	v_cvt_pk_bf16_f32 v16, v10, v11
	v_cvt_pk_bf16_f32 v17, v12, v13
	s_mov_b64 s[2:3], 0xb0000
	v_cvt_pk_bf16_f32 v113, v108, v109
	v_lshlrev_b64 v[106:107], 12, v[106:107]
	v_ashrrev_i32_e32 v91, 31, v90
	v_cvt_pk_bf16_f32 v78, v78, v79
	v_cvt_pk_bf16_f32 v79, v80, v81
	v_cvt_pk_bf16_f32 v80, v74, v75
	v_or_b32_e32 v74, 48, v146
	v_addc_co_u32_e32 v33, vcc, 0, v151, vcc
	global_store_dwordx4 v[30:31], v[14:17], off offset:256
	global_store_dwordx4 v[150:151], v[110:113], off offset:256
	v_cvt_pk_bf16_f32 v97, v92, v93
	v_lshl_add_u64 v[14:15], v[150:151], 0, s[2:3]
	s_mov_b32 s2, 0xb0000
	v_lshl_add_u64 v[110:111], v[148:149], 0, v[106:107]
	v_lshlrev_b64 v[90:91], 12, v[90:91]
	v_ashrrev_i32_e32 v75, 31, v74
	v_add_co_u32_e32 v16, vcc, s2, v150
	global_store_dwordx4 v[110:111], v[94:97], off offset:256
	v_cvt_pk_bf16_f32 v81, v76, v77
	v_lshlrev_b64 v[74:75], 12, v[74:75]
	v_lshl_add_u64 v[94:95], v[148:149], 0, v[90:91]
	v_addc_co_u32_e32 v17, vcc, 0, v151, vcc
	v_cvt_pk_bf16_f32 v126, v126, v127
	v_cvt_pk_bf16_f32 v127, v128, v129
	v_cvt_pk_bf16_f32 v128, v122, v123
	v_cvt_pk_bf16_f32 v129, v124, v125
	v_cvt_pk_bf16_f32 v106, v118, v119
	v_cvt_pk_bf16_f32 v107, v120, v121
	v_cvt_pk_bf16_f32 v108, v114, v115
	v_cvt_pk_bf16_f32 v109, v116, v117
	v_cvt_pk_bf16_f32 v90, v102, v103
	v_cvt_pk_bf16_f32 v91, v104, v105
	v_cvt_pk_bf16_f32 v92, v98, v99
	v_cvt_pk_bf16_f32 v93, v100, v101
	global_store_dwordx4 v[94:95], v[78:81], off offset:256
	v_cvt_pk_bf16_f32 v76, v82, v83
	v_cvt_pk_bf16_f32 v77, v84, v85
	v_lshl_add_u64 v[78:79], v[148:149], 0, v[74:75]
	v_cvt_pk_bf16_f32 v74, v86, v87
	v_cvt_pk_bf16_f32 v75, v88, v89
	v_cvt_pk_bf16_f32 v73, v68, v69
	v_cvt_pk_bf16_f32 v65, v60, v61
	v_cvt_pk_bf16_f32 v42, v54, v55
	v_cvt_pk_bf16_f32 v43, v56, v57
	v_cvt_pk_bf16_f32 v44, v50, v51
	v_cvt_pk_bf16_f32 v45, v52, v53
	v_cvt_pk_bf16_f32 v26, v38, v39
	v_cvt_pk_bf16_f32 v27, v40, v41
	v_cvt_pk_bf16_f32 v28, v34, v35
	v_cvt_pk_bf16_f32 v29, v36, v37
	v_cvt_pk_bf16_f32 v10, v22, v23
	v_cvt_pk_bf16_f32 v11, v24, v25
	v_cvt_pk_bf16_f32 v12, v18, v19
	v_cvt_pk_bf16_f32 v13, v20, v21
	v_cvt_pk_bf16_f32 v6, v6, v7
	v_cvt_pk_bf16_f32 v7, v8, v9
	v_cvt_pk_bf16_f32 v8, v2, v3
	v_cvt_pk_bf16_f32 v9, v4, v5
	s_and_b64 vcc, exec, s[0:1]
	s_mov_b32 s46, s6
	s_mov_b32 s4, s8
	s_mov_b64 s[14:15], s[12:13]
	s_mov_b64 s[16:17], s[10:11]
	s_mov_b32 s39, 0xb2a5705f
	global_store_dwordx4 v[150:151], v[126:129], off
	global_store_dwordx4 v[110:111], v[106:109], off
	global_store_dwordx4 v[94:95], v[90:93], off
	global_store_dwordx4 v[78:79], v[74:77], off
	global_store_dwordx4 v[78:79], v[70:73], off offset:256
	global_store_dwordx4 v[58:59], v[62:65], off
	global_store_dwordx4 v[48:49], v[42:45], off
	global_store_dwordx4 v[32:33], v[26:29], off
	global_store_dwordx4 v[16:17], v[10:13], off
	global_store_dwordx4 v[14:15], v[6:9], off offset:256
	s_cbranch_vccz .LBB0_392
	s_waitcnt vmcnt(0)
	s_cmpk_gt_u32 s20, 0xff
	v_readlane_b32 s31, v254, 22
	v_readlane_b32 s33, v254, 23
	s_mov_b32 s41, 0xe020
	s_cbranch_scc1 .LBB0_401
	s_barrier

; #define PG8_STAGE(bufoff, gbase, voff) do { _Pragma("unroll") for (int _i = 0; _i < 2; ++_i) \
;         __builtin_amdgcn_global_load_lds((const unsigned*)((const char*)(gbase) + (voff)[_i]), (LAS unsigned*)(lds + (bufoff) + ldsw + _i * 8192), 16, 0, 0); } while (0)
; #define PG8_LDA(dst, b, h) do { _Pragma("unroll") for (int m = 0; m < 4; ++m) _Pragma("unroll") for (int k = 0; k < 2; ++k) dst[m][k] = *(const LAS bf16x8*)(lds + PG8_SA(b, h) + aoff + m * 2048 + k * 1024); } while (0)
; #define PG8_LDB(dst, b, h) do { _Pragma("unroll") for (int n = 0; n < 2; ++n) _Pragma("unroll") for (int k = 0; k < 2; ++k) dst[n][k] = *(const LAS bf16x8*)(lds + PG8_SB(b, h) + boff + n * 2048 + k * 1024); } while (0)
; #define PG8_MMA(ai, bj, At, Bt) do { __builtin_amdgcn_s_setprio(1); _Pragma("unroll") for (int m = 0; m < 4; ++m) _Pragma("unroll") for (int n = 0; n < 2; ++n) _Pragma("unroll") for (int k = 0; k < 2; ++k) \
;         acc[ai][bj][m][n] = __builtin_amdgcn_mfma_f32_16x16x32_bf16(Bt[n][k], At[m][k], acc[ai][bj][m][n], 0, 0, 0); __builtin_amdgcn_s_setprio(0); } while (0)
; #define PG8_WAIT_V(n) asm volatile("s_waitcnt vmcnt(" #n ")" ::: "memory")
; #define PG8_WAIT_L(n) asm volatile("s_waitcnt lgkmcnt(" #n ")" ::: "memory")
; #define PG8_BAR __builtin_amdgcn_s_barrier()
; #define PG8_SCHED __builtin_amdgcn_sched_barrier(0)
; template <class Epi, class Sched, bool AREMAP>
; __device__ __forceinline__ void gemm_phase(LAS unsigned char* lds, const Gemm g, const Sched& S, const Epi& E, int wv) {
;     ...
;             PG8_LDB(B0, 0, 0); PG8_SCHED; PG8_LDA(At, 0, 0); PG8_STAGE(PG8_SA(1, 1), a1 + hstepA, voffA);
;             PG8_WAIT_L(8); PG8_BAR; PG8_WAIT_L(0); PG8_MMA(0, 0, At, B0); PG8_BAR; PG8_SCHED;
;             PG8_LDB(B1, 0, 1); PG8_STAGE(PG8_SB(0, 0), b2, voffB);
;             PG8_BAR; PG8_WAIT_L(0); PG8_MMA(0, 1, At, B1); PG8_BAR;
;             PG8_LDA(At, 0, 1); PG8_STAGE(PG8_SA(0, 0), a2, voffA);
;             PG8_BAR; PG8_WAIT_L(0); PG8_MMA(1, 0, At, B0); PG8_BAR; PG8_SCHED;
;             PG8_STAGE(PG8_SB(0, 1), b2 + hstepB, voffB);
;             PG8_WAIT_V(6); PG8_BAR; PG8_MMA(1, 1, At, B1); PG8_BAR;
.LBB0_426:
	s_add_u32 s20, s18, 0xfff80080
	s_addc_u32 s21, s19, -1
	s_add_i32 s38, 0, 0x10000
	v_add_u32_e32 v142, s38, v186
	ds_read_b128 v[130:133], v142
	ds_read_b128 v[134:137], v142 offset:1024
	ds_read_b128 v[138:141], v142 offset:2048
	ds_read_b128 v[142:145], v142 offset:3072
	s_cmp_eq_u32 s46, 28
	s_cselect_b32 s23, s3, s21
	s_cselect_b32 s22, s5, s20
	s_cselect_b32 s21, s11, s37
	s_cselect_b32 s20, s13, s36
	s_add_i32 m0, s35, 0xc000
	ds_read_b128 v[146:149], v196
	ds_read_b128 v[150:153], v196 offset:1024
	ds_read_b128 v[154:157], v196 offset:2048
	ds_read_b128 v[158:161], v196 offset:3072
	ds_read_b128 v[174:177], v196 offset:4096
	ds_read_b128 v[178:181], v196 offset:5120
	ds_read_b128 v[182:185], v196 offset:6144
	ds_read_b128 v[192:195], v196 offset:7168
	global_load_lds_dwordx4 v172, s[18:19]
	s_add_i32 m0, s35, 0xe000
	s_nop 0
	global_load_lds_dwordx4 v170, s[18:19]
	s_waitcnt lgkmcnt(8)
	s_barrier
	s_waitcnt lgkmcnt(0)
	s_waitcnt lgkmcnt(0)
	v_mfma_f32_16x16x32_bf16 v[126:129], v[130:133], v[146:149], v[126:129]
	v_mfma_f32_16x16x32_bf16 v[122:125], v[138:141], v[146:149], v[122:125]
	v_mfma_f32_16x16x32_bf16 v[110:113], v[130:133], v[154:157], v[110:113]
	v_mfma_f32_16x16x32_bf16 v[106:109], v[138:141], v[154:157], v[106:109]
	v_mfma_f32_16x16x32_bf16 v[94:97], v[130:133], v[174:177], v[94:97]
	v_mfma_f32_16x16x32_bf16 v[90:93], v[138:141], v[174:177], v[90:93]
	v_mfma_f32_16x16x32_bf16 v[78:81], v[130:133], v[182:185], v[78:81]
	v_mfma_f32_16x16x32_bf16 v[74:77], v[138:141], v[182:185], v[74:77]
	v_mfma_f32_16x16x32_bf16 v[126:129], v[134:137], v[150:153], v[126:129]
	v_mfma_f32_16x16x32_bf16 v[122:125], v[142:145], v[150:153], v[122:125]
	v_mfma_f32_16x16x32_bf16 v[110:113], v[134:137], v[158:161], v[110:113]
	v_mfma_f32_16x16x32_bf16 v[106:109], v[142:145], v[158:161], v[106:109]
	v_mfma_f32_16x16x32_bf16 v[94:97], v[134:137], v[178:181], v[94:97]
	v_mfma_f32_16x16x32_bf16 v[90:93], v[142:145], v[178:181], v[90:93]
	v_mfma_f32_16x16x32_bf16 v[78:81], v[134:137], v[192:195], v[78:81]
	v_mfma_f32_16x16x32_bf16 v[74:77], v[142:145], v[192:195], v[74:77]
	s_barrier
	s_add_i32 s39, 0, 0x14000
	s_add_i32 s38, s38, s34
	v_add_u32_e32 v197, s39, v186
	s_add_u32 s80, s20, 0x80
	s_addc_u32 s81, s21, 0
	s_mov_b32 m0, s38
	ds_read_b128 v[198:201], v197
	ds_read_b128 v[202:205], v197 offset:1024
	ds_read_b128 v[206:209], v197 offset:2048
	ds_read_b128 v[210:213], v197 offset:3072
	global_load_lds_dwordx4 v164, s[20:21]
	s_add_i32 m0, s38, 0x2000
	s_nop 0
	global_load_lds_dwordx4 v168, s[20:21]
	s_barrier
	s_waitcnt lgkmcnt(0)
	s_waitcnt lgkmcnt(0)
	v_mfma_f32_16x16x32_bf16 v[118:121], v[198:201], v[146:149], v[118:121]
	v_mfma_f32_16x16x32_bf16 v[114:117], v[206:209], v[146:149], v[114:117]
	v_mfma_f32_16x16x32_bf16 v[102:105], v[198:201], v[154:157], v[102:105]
	v_mfma_f32_16x16x32_bf16 v[98:101], v[206:209], v[154:157], v[98:101]
	v_mfma_f32_16x16x32_bf16 v[86:89], v[198:201], v[174:177], v[86:89]
	v_mfma_f32_16x16x32_bf16 v[82:85], v[206:209], v[174:177], v[82:85]
	v_mfma_f32_16x16x32_bf16 v[70:73], v[198:201], v[182:185], v[70:73]
	v_mfma_f32_16x16x32_bf16 v[66:69], v[206:209], v[182:185], v[66:69]
	v_mfma_f32_16x16x32_bf16 v[118:121], v[202:205], v[150:153], v[118:121]
	v_mfma_f32_16x16x32_bf16 v[114:117], v[210:213], v[150:153], v[114:117]
	v_mfma_f32_16x16x32_bf16 v[102:105], v[202:205], v[158:161], v[102:105]
	v_mfma_f32_16x16x32_bf16 v[98:101], v[210:213], v[158:161], v[98:101]
	v_mfma_f32_16x16x32_bf16 v[86:89], v[202:205], v[178:181], v[86:89]
	v_mfma_f32_16x16x32_bf16 v[82:85], v[210:213], v[178:181], v[82:85]
	v_mfma_f32_16x16x32_bf16 v[70:73], v[202:205], v[192:195], v[70:73]
	v_mfma_f32_16x16x32_bf16 v[66:69], v[210:213], v[192:195], v[66:69]
	s_mov_b32 m0, s35
	s_add_u32 s96, s22, 0x80
	s_addc_u32 s97, s23, 0
	s_barrier
	ds_read_b128 v[146:149], v196 offset:16384
	ds_read_b128 v[150:153], v196 offset:17408
	ds_read_b128 v[154:157], v196 offset:18432
	ds_read_b128 v[158:161], v196 offset:19456
	ds_read_b128 v[174:177], v196 offset:20480
	ds_read_b128 v[178:181], v196 offset:21504
	ds_read_b128 v[182:185], v196 offset:22528
	ds_read_b128 v[192:195], v196 offset:23552
	global_load_lds_dwordx4 v162, s[22:23]
	s_mov_b32 m0, s41
	s_nop 0
	global_load_lds_dwordx4 v166, s[22:23]
	s_barrier
	s_waitcnt lgkmcnt(0)
	s_waitcnt lgkmcnt(0)
	v_mfma_f32_16x16x32_bf16 v[62:65], v[130:133], v[146:149], v[62:65]
	v_mfma_f32_16x16x32_bf16 v[58:61], v[138:141], v[146:149], v[58:61]
	v_mfma_f32_16x16x32_bf16 v[46:49], v[130:133], v[154:157], v[46:49]
	v_mfma_f32_16x16x32_bf16 v[42:45], v[138:141], v[154:157], v[42:45]
	v_mfma_f32_16x16x32_bf16 v[30:33], v[130:133], v[174:177], v[30:33]
	v_mfma_f32_16x16x32_bf16 v[26:29], v[138:141], v[174:177], v[26:29]
	v_mfma_f32_16x16x32_bf16 v[14:17], v[130:133], v[182:185], v[14:17]
	v_mfma_f32_16x16x32_bf16 v[10:13], v[138:141], v[182:185], v[10:13]
	v_mfma_f32_16x16x32_bf16 v[62:65], v[134:137], v[150:153], v[62:65]
	v_mfma_f32_16x16x32_bf16 v[58:61], v[142:145], v[150:153], v[58:61]
	v_mfma_f32_16x16x32_bf16 v[46:49], v[134:137], v[158:161], v[46:49]
	v_mfma_f32_16x16x32_bf16 v[42:45], v[142:145], v[158:161], v[42:45]
	v_mfma_f32_16x16x32_bf16 v[30:33], v[134:137], v[178:181], v[30:33]
	v_mfma_f32_16x16x32_bf16 v[26:29], v[142:145], v[178:181], v[26:29]
	v_mfma_f32_16x16x32_bf16 v[14:17], v[134:137], v[192:195], v[14:17]
	v_mfma_f32_16x16x32_bf16 v[10:13], v[142:145], v[192:195], v[10:13]
	s_barrier
	s_add_u32 s66, s20, 0x80000
	s_addc_u32 s67, s21, 0
	s_add_i32 s38, s39, s34
	s_mov_b32 m0, s38
	s_nop 0
	global_load_lds_dwordx4 v164, s[66:67]
	s_add_i32 m0, s38, 0x2000
	s_nop 0
	global_load_lds_dwordx4 v168, s[66:67]
	s_waitcnt vmcnt(6)
	s_barrier
; #define PG8_STAGE(bufoff, gbase, voff) do { _Pragma("unroll") for (int _i = 0; _i < 2; ++_i) \
;         __builtin_amdgcn_global_load_lds((const unsigned*)((const char*)(gbase) + (voff)[_i]), (LAS unsigned*)(lds + (bufoff) + ldsw + _i * 8192), 16, 0, 0); } while (0)
; #define PG8_LDA(dst, b, h) do { _Pragma("unroll") for (int m = 0; m < 4; ++m) _Pragma("unroll") for (int k = 0; k < 2; ++k) dst[m][k] = *(const LAS bf16x8*)(lds + PG8_SA(b, h) + aoff + m * 2048 + k * 1024); } while (0)
; #define PG8_LDB(dst, b, h) do { _Pragma("unroll") for (int n = 0; n < 2; ++n) _Pragma("unroll") for (int k = 0; k < 2; ++k) dst[n][k] = *(const LAS bf16x8*)(lds + PG8_SB(b, h) + boff + n * 2048 + k * 1024); } while (0)
; #define PG8_MMA(ai, bj, At, Bt) do { __builtin_amdgcn_s_setprio(1); _Pragma("unroll") for (int m = 0; m < 4; ++m) _Pragma("unroll") for (int n = 0; n < 2; ++n) _Pragma("unroll") for (int k = 0; k < 2; ++k) \
;         acc[ai][bj][m][n] = __builtin_amdgcn_mfma_f32_16x16x32_bf16(Bt[n][k], At[m][k], acc[ai][bj][m][n], 0, 0, 0); __builtin_amdgcn_s_setprio(0); } while (0)
; #define PG8_WAIT_V(n) asm volatile("s_waitcnt vmcnt(" #n ")" ::: "memory")
; #define PG8_WAIT_L(n) asm volatile("s_waitcnt lgkmcnt(" #n ")" ::: "memory")
; #define PG8_BAR __builtin_amdgcn_s_barrier()
; #define PG8_SCHED __builtin_amdgcn_sched_barrier(0)
; template <class Epi, class Sched, bool AREMAP>
; __device__ __forceinline__ void gemm_phase(LAS unsigned char* lds, const Gemm g, const Sched& S, const Epi& E, int wv) {
;     ...
;             PG8_WAIT_V(6); PG8_BAR; PG8_MMA(1, 1, At, B1); PG8_BAR;
;             PG8_LDB(B0, 1, 0); PG8_SCHED; PG8_LDA(At, 1, 0); PG8_STAGE(PG8_SA(0, 1), a2 + hstepA, voffA);
;             PG8_WAIT_L(8); PG8_BAR; PG8_WAIT_L(0); PG8_MMA(0, 0, At, B0); PG8_BAR; PG8_SCHED;
;             PG8_LDB(B1, 1, 1); PG8_STAGE(PG8_SB(1, 0), b3, voffB);
;             PG8_BAR; PG8_WAIT_L(0); PG8_MMA(0, 1, At, B1); PG8_BAR;
	v_mfma_f32_16x16x32_bf16 v[54:57], v[198:201], v[146:149], v[54:57]
	v_mfma_f32_16x16x32_bf16 v[50:53], v[206:209], v[146:149], v[50:53]
	v_mfma_f32_16x16x32_bf16 v[38:41], v[198:201], v[154:157], v[38:41]
	v_mfma_f32_16x16x32_bf16 v[34:37], v[206:209], v[154:157], v[34:37]
	v_mfma_f32_16x16x32_bf16 v[22:25], v[198:201], v[174:177], v[22:25]
	v_mfma_f32_16x16x32_bf16 v[18:21], v[206:209], v[174:177], v[18:21]
	v_mfma_f32_16x16x32_bf16 v[6:9], v[198:201], v[182:185], v[6:9]
	v_mfma_f32_16x16x32_bf16 v[2:5], v[206:209], v[182:185], v[2:5]
	v_mfma_f32_16x16x32_bf16 v[54:57], v[202:205], v[150:153], v[54:57]
	v_mfma_f32_16x16x32_bf16 v[50:53], v[210:213], v[150:153], v[50:53]
	v_mfma_f32_16x16x32_bf16 v[38:41], v[202:205], v[158:161], v[38:41]
	v_mfma_f32_16x16x32_bf16 v[34:37], v[210:213], v[158:161], v[34:37]
	v_mfma_f32_16x16x32_bf16 v[22:25], v[202:205], v[178:181], v[22:25]
	v_mfma_f32_16x16x32_bf16 v[18:21], v[210:213], v[178:181], v[18:21]
	v_mfma_f32_16x16x32_bf16 v[6:9], v[202:205], v[192:195], v[6:9]
	v_mfma_f32_16x16x32_bf16 v[2:5], v[210:213], v[192:195], v[2:5]
	s_add_i32 s38, 0, 0x18000
	v_add_u32_e32 v142, s38, v186
	s_barrier
	ds_read_b128 v[130:133], v142
	ds_read_b128 v[134:137], v142 offset:1024
	ds_read_b128 v[138:141], v142 offset:2048
	ds_read_b128 v[142:145], v142 offset:3072
	s_add_u32 s22, s22, 0x80000
	s_addc_u32 s23, s23, 0
	s_mov_b32 m0, s52
	ds_read_b128 v[146:149], v196 offset:32768
	ds_read_b128 v[150:153], v196 offset:33792
	ds_read_b128 v[154:157], v196 offset:34816
	ds_read_b128 v[158:161], v196 offset:35840
	ds_read_b128 v[174:177], v196 offset:36864
	ds_read_b128 v[178:181], v196 offset:37888
	ds_read_b128 v[182:185], v196 offset:38912
	ds_read_b128 v[192:195], v196 offset:39936
	global_load_lds_dwordx4 v162, s[22:23]
	s_mov_b32 m0, s53
	s_nop 0
	global_load_lds_dwordx4 v166, s[22:23]
	s_waitcnt lgkmcnt(8)
	s_barrier
	s_waitcnt lgkmcnt(0)
	s_waitcnt lgkmcnt(0)
	v_mfma_f32_16x16x32_bf16 v[126:129], v[130:133], v[146:149], v[126:129]
	v_mfma_f32_16x16x32_bf16 v[122:125], v[138:141], v[146:149], v[122:125]
	v_mfma_f32_16x16x32_bf16 v[110:113], v[130:133], v[154:157], v[110:113]
	v_mfma_f32_16x16x32_bf16 v[106:109], v[138:141], v[154:157], v[106:109]
	v_mfma_f32_16x16x32_bf16 v[94:97], v[130:133], v[174:177], v[94:97]
	v_mfma_f32_16x16x32_bf16 v[90:93], v[138:141], v[174:177], v[90:93]
	v_mfma_f32_16x16x32_bf16 v[78:81], v[130:133], v[182:185], v[78:81]
	v_mfma_f32_16x16x32_bf16 v[74:77], v[138:141], v[182:185], v[74:77]
	v_mfma_f32_16x16x32_bf16 v[126:129], v[134:137], v[150:153], v[126:129]
	v_mfma_f32_16x16x32_bf16 v[122:125], v[142:145], v[150:153], v[122:125]
	v_mfma_f32_16x16x32_bf16 v[110:113], v[134:137], v[158:161], v[110:113]
	v_mfma_f32_16x16x32_bf16 v[106:109], v[142:145], v[158:161], v[106:109]
	v_mfma_f32_16x16x32_bf16 v[94:97], v[134:137], v[178:181], v[94:97]
	v_mfma_f32_16x16x32_bf16 v[90:93], v[142:145], v[178:181], v[90:93]
	v_mfma_f32_16x16x32_bf16 v[78:81], v[134:137], v[192:195], v[78:81]
	v_mfma_f32_16x16x32_bf16 v[74:77], v[142:145], v[192:195], v[74:77]
	s_barrier
	s_add_i32 s22, 0, 0x1c000
	s_add_i32 s23, s38, s34
	v_add_u32_e32 v197, s22, v186
	s_mov_b32 m0, s23
	ds_read_b128 v[198:201], v197
	ds_read_b128 v[202:205], v197 offset:1024
	ds_read_b128 v[206:209], v197 offset:2048
	ds_read_b128 v[210:213], v197 offset:3072
	global_load_lds_dwordx4 v164, s[80:81]
	s_add_i32 m0, s23, 0x2000
	s_nop 0
	global_load_lds_dwordx4 v168, s[80:81]
	s_barrier
	s_waitcnt lgkmcnt(0)
	s_waitcnt lgkmcnt(0)
	v_mfma_f32_16x16x32_bf16 v[118:121], v[198:201], v[146:149], v[118:121]
	v_mfma_f32_16x16x32_bf16 v[114:117], v[206:209], v[146:149], v[114:117]
	v_mfma_f32_16x16x32_bf16 v[102:105], v[198:201], v[154:157], v[102:105]
	v_mfma_f32_16x16x32_bf16 v[98:101], v[206:209], v[154:157], v[98:101]
	v_mfma_f32_16x16x32_bf16 v[86:89], v[198:201], v[174:177], v[86:89]
	v_mfma_f32_16x16x32_bf16 v[82:85], v[206:209], v[174:177], v[82:85]
	v_mfma_f32_16x16x32_bf16 v[70:73], v[198:201], v[182:185], v[70:73]
	v_mfma_f32_16x16x32_bf16 v[66:69], v[206:209], v[182:185], v[66:69]
	v_mfma_f32_16x16x32_bf16 v[118:121], v[202:205], v[150:153], v[118:121]
	v_mfma_f32_16x16x32_bf16 v[114:117], v[210:213], v[150:153], v[114:117]
	v_mfma_f32_16x16x32_bf16 v[102:105], v[202:205], v[158:161], v[102:105]
	v_mfma_f32_16x16x32_bf16 v[98:101], v[210:213], v[158:161], v[98:101]
	v_mfma_f32_16x16x32_bf16 v[86:89], v[202:205], v[178:181], v[86:89]
	v_mfma_f32_16x16x32_bf16 v[82:85], v[210:213], v[178:181], v[82:85]
	v_mfma_f32_16x16x32_bf16 v[70:73], v[202:205], v[192:195], v[70:73]
	v_mfma_f32_16x16x32_bf16 v[66:69], v[210:213], v[192:195], v[66:69]
	s_mov_b32 m0, s57
	s_barrier
; __device__ __forceinline__ int otid(int wv) { int t = (wv << 6) | (int)__builtin_amdgcn_mbcnt_hi(~0u, __builtin_amdgcn_mbcnt_lo(~0u, 0u)); asm volatile("" : "+v"(t)); return t; }
; #define PG8_STAGE(bufoff, gbase, voff) do { _Pragma("unroll") for (int _i = 0; _i < 2; ++_i) \
;         __builtin_amdgcn_global_load_lds((const unsigned*)((const char*)(gbase) + (voff)[_i]), (LAS unsigned*)(lds + (bufoff) + ldsw + _i * 8192), 16, 0, 0); } while (0)
; #define PG8_LDA(dst, b, h) do { _Pragma("unroll") for (int m = 0; m < 4; ++m) _Pragma("unroll") for (int k = 0; k < 2; ++k) dst[m][k] = *(const LAS bf16x8*)(lds + PG8_SA(b, h) + aoff + m * 2048 + k * 1024); } while (0)
; #define PG8_WAIT_V(n) asm volatile("s_waitcnt vmcnt(" #n ")" ::: "memory")
; #define PG8_BAR __builtin_amdgcn_s_barrier()
; template <class Epi, class Sched, bool AREMAP>
; __device__ __forceinline__ void gemm_phase(LAS unsigned char* lds, const Gemm g, const Sched& S, const Epi& E, int wv) {
;     ...
;             PG8_BAR; PG8_WAIT_L(0); PG8_MMA(0, 1, At, B1); PG8_BAR;
;             PG8_LDA(At, 1, 1); PG8_STAGE(PG8_SA(1, 0), a3, voffA);
;             PG8_BAR; PG8_WAIT_L(0); PG8_MMA(1, 0, At, B0); PG8_BAR; PG8_SCHED;
;             PG8_STAGE(PG8_SB(1, 1), b3 + hstepB, voffB);
;             PG8_WAIT_V(6); PG8_BAR; PG8_MMA(1, 1, At, B1); PG8_BAR;
;     __device__ __forceinline__ void operator()(const f32x4 (&acc)[2][2][4][2], const Unit& u, int wr, int wc, int fr, int fq) const {
;         const int b = u.pn >> 3, pn8 = u.pn & 7;
;         const int row0 = u.pm * BM + wr * 64 + fr, col0 = pn8 * BM + wc * 32 + 8 * fq;
;         const bf16_t* yb = YB + (size_t)b * NTOK * DM;
;         u32x4* sc = (u32x4*)scratch + otid(wv);
; #pragma unroll
;         for (int ai = 0; ai < 2; ++ai)
; #pragma unroll
;             for (int mp = 0; mp < 2; ++mp) {
;                 u32x4 y[2][2], pr[2][2];
; #pragma unroll
;                 for (int mm = 0; mm < 2; ++mm)
; #pragma unroll
;                     for (int bj = 0; bj < 2; ++bj) { const int m = mp * 2 + mm; const size_t off = (size_t)(row0 + ai * HALF + m * 16) * DM + col0;
;                         y[mm][bj] = *(const u32x4*)(yb + off + bj * HALF);
;                         const int slot = (ai * 4 + m) * 2 + bj;
;                         pr[mm][bj] = (u32x4){0u, 0u, 0u, 0u};
;                         if (b > 0) pr[mm][bj] = sc[(size_t)slot * NTHR]; }
	ds_read_b128 v[146:149], v196 offset:49152
	ds_read_b128 v[150:153], v196 offset:50176
	ds_read_b128 v[154:157], v196 offset:51200
	ds_read_b128 v[158:161], v196 offset:52224
	ds_read_b128 v[174:177], v196 offset:53248
	ds_read_b128 v[178:181], v196 offset:54272
	ds_read_b128 v[182:185], v196 offset:55296
	ds_read_b128 v[192:195], v196 offset:56320
	global_load_lds_dwordx4 v162, s[96:97]
	s_mov_b32 m0, s62
	s_nop 0
	global_load_lds_dwordx4 v166, s[96:97]
	s_barrier
	s_waitcnt lgkmcnt(0)
	s_waitcnt lgkmcnt(0)
	v_mfma_f32_16x16x32_bf16 v[62:65], v[130:133], v[146:149], v[62:65]
	v_mfma_f32_16x16x32_bf16 v[58:61], v[138:141], v[146:149], v[58:61]
	v_mfma_f32_16x16x32_bf16 v[46:49], v[130:133], v[154:157], v[46:49]
	v_mfma_f32_16x16x32_bf16 v[42:45], v[138:141], v[154:157], v[42:45]
	v_mfma_f32_16x16x32_bf16 v[30:33], v[130:133], v[174:177], v[30:33]
	v_mfma_f32_16x16x32_bf16 v[26:29], v[138:141], v[174:177], v[26:29]
	v_mfma_f32_16x16x32_bf16 v[14:17], v[130:133], v[182:185], v[14:17]
	v_mfma_f32_16x16x32_bf16 v[10:13], v[138:141], v[182:185], v[10:13]
	v_mfma_f32_16x16x32_bf16 v[62:65], v[134:137], v[150:153], v[62:65]
	v_mfma_f32_16x16x32_bf16 v[58:61], v[142:145], v[150:153], v[58:61]
	v_mfma_f32_16x16x32_bf16 v[46:49], v[134:137], v[158:161], v[46:49]
	v_mfma_f32_16x16x32_bf16 v[42:45], v[142:145], v[158:161], v[42:45]
	v_mfma_f32_16x16x32_bf16 v[30:33], v[134:137], v[178:181], v[30:33]
	v_mfma_f32_16x16x32_bf16 v[26:29], v[142:145], v[178:181], v[26:29]
	v_mfma_f32_16x16x32_bf16 v[14:17], v[134:137], v[192:195], v[14:17]
	v_mfma_f32_16x16x32_bf16 v[10:13], v[142:145], v[192:195], v[10:13]
	s_barrier
	s_add_u32 s20, s20, 0x80080
	s_addc_u32 s21, s21, 0
	s_add_i32 s22, s22, s34
	s_mov_b32 m0, s22
	s_nop 0
	global_load_lds_dwordx4 v164, s[20:21]
	s_add_i32 m0, s22, 0x2000
	s_nop 0
	global_load_lds_dwordx4 v168, s[20:21]
	s_waitcnt vmcnt(6)
	s_barrier
	v_mfma_f32_16x16x32_bf16 v[54:57], v[198:201], v[146:149], v[54:57]
	v_mfma_f32_16x16x32_bf16 v[50:53], v[206:209], v[146:149], v[50:53]
	v_mfma_f32_16x16x32_bf16 v[38:41], v[198:201], v[154:157], v[38:41]
	v_mfma_f32_16x16x32_bf16 v[34:37], v[206:209], v[154:157], v[34:37]
	v_mfma_f32_16x16x32_bf16 v[22:25], v[198:201], v[174:177], v[22:25]
	v_mfma_f32_16x16x32_bf16 v[18:21], v[206:209], v[174:177], v[18:21]
	v_mfma_f32_16x16x32_bf16 v[6:9], v[198:201], v[182:185], v[6:9]
	v_mfma_f32_16x16x32_bf16 v[2:5], v[206:209], v[182:185], v[2:5]
	v_mfma_f32_16x16x32_bf16 v[54:57], v[202:205], v[150:153], v[54:57]
	v_mfma_f32_16x16x32_bf16 v[50:53], v[210:213], v[150:153], v[50:53]
	v_mfma_f32_16x16x32_bf16 v[38:41], v[202:205], v[158:161], v[38:41]
	v_mfma_f32_16x16x32_bf16 v[34:37], v[210:213], v[158:161], v[34:37]
	v_mfma_f32_16x16x32_bf16 v[22:25], v[202:205], v[178:181], v[22:25]
	v_mfma_f32_16x16x32_bf16 v[18:21], v[210:213], v[178:181], v[18:21]
	v_mfma_f32_16x16x32_bf16 v[6:9], v[202:205], v[192:195], v[6:9]
	v_mfma_f32_16x16x32_bf16 v[2:5], v[210:213], v[192:195], v[2:5]
	s_add_i32 s46, s46, 2
	s_add_u32 s36, s36, 0x100
	s_addc_u32 s37, s37, 0
	s_add_u32 s18, s18, 0x100
	s_addc_u32 s19, s19, 0
	s_cmp_gt_u32 s46, 29
	s_barrier
	s_cbranch_scc0 .LBB0_426
	s_ashr_i32 s18, s4, 3
	v_lshl_add_u32 v178, s2, 8, v1
	s_lshl_b32 s2, s4, 8
	s_and_b32 s2, s2, 0x700
	s_ashr_i32 s19, s18, 31
	v_or_b32_e32 v132, s2, v187
	s_lshl_b64 s[2:3], s[18:19], 27
	s_add_u32 s2, s55, s2
	s_addc_u32 s3, s56, s3
	v_mov_b32_e32 v130, v236
	v_lshlrev_b32_e32 v176, 1, v132
	v_mov_b32_e32 v177, v0
	v_ashrrev_i32_e32 v179, 31, v178
	v_lshl_add_u64 v[180:181], s[2:3], 0, v[176:177]
	v_ashrrev_i32_e32 v131, 31, v130
	v_lshlrev_b64 v[184:185], 12, v[178:179]
	v_lshl_add_u64 v[174:175], v[130:131], 4, s[6:7]
	v_lshl_add_u64 v[130:131], v[180:181], 0, v[184:185]
	v_mov_b64_e32 v[250:251], v[130:131]
	s_mov_b32 s20, 0x20000
	s_mov_b32 s21, 0
	v_lshl_add_u64 v[252:253], v[250:251], 0, s[20:21]
	global_load_dwordx4 v[198:201], v[252:253], off
	global_load_dwordx4 v[202:205], v[252:253], off offset:256
	s_mov_b32 s20, 0x30000
	v_lshl_add_u64 v[252:253], v[250:251], 0, s[20:21]
	global_load_dwordx4 v[206:209], v[252:253], off
	global_load_dwordx4 v[210:213], v[252:253], off offset:256
	global_load_dwordx4 v[154:157], v[130:131], off
	s_cmp_gt_i32 s18, 0
	s_cselect_b64 s[2:3], -1, 0
	s_cmp_lt_i32 s18, 1
	s_cbranch_scc1 .LBB0_429
	global_load_dwordx4 v[158:161], v[174:175], off
	s_branch .LBB0_430

; #define PG8_STAGE(bufoff, gbase, voff) do { _Pragma("unroll") for (int _i = 0; _i < 2; ++_i) \
;         __builtin_amdgcn_global_load_lds((const unsigned*)((const char*)(gbase) + (voff)[_i]), (LAS unsigned*)(lds + (bufoff) + ldsw + _i * 8192), 16, 0, 0); } while (0)
; #define PG8_LDA(dst, b, h) do { _Pragma("unroll") for (int m = 0; m < 4; ++m) _Pragma("unroll") for (int k = 0; k < 2; ++k) dst[m][k] = *(const LAS bf16x8*)(lds + PG8_SA(b, h) + aoff + m * 2048 + k * 1024); } while (0)
; #define PG8_LDB(dst, b, h) do { _Pragma("unroll") for (int n = 0; n < 2; ++n) _Pragma("unroll") for (int k = 0; k < 2; ++k) dst[n][k] = *(const LAS bf16x8*)(lds + PG8_SB(b, h) + boff + n * 2048 + k * 1024); } while (0)
; #define PG8_MMA(ai, bj, At, Bt) do { __builtin_amdgcn_s_setprio(1); _Pragma("unroll") for (int m = 0; m < 4; ++m) _Pragma("unroll") for (int n = 0; n < 2; ++n) _Pragma("unroll") for (int k = 0; k < 2; ++k) \
;         acc[ai][bj][m][n] = __builtin_amdgcn_mfma_f32_16x16x32_bf16(Bt[n][k], At[m][k], acc[ai][bj][m][n], 0, 0, 0); __builtin_amdgcn_s_setprio(0); } while (0)
; #define PG8_WAIT_V(n) asm volatile("s_waitcnt vmcnt(" #n ")" ::: "memory")
; #define PG8_WAIT_L(n) asm volatile("s_waitcnt lgkmcnt(" #n ")" ::: "memory")
; #define PG8_BAR __builtin_amdgcn_s_barrier()
; #define PG8_SCHED __builtin_amdgcn_sched_barrier(0)
; template <class Epi, class Sched, bool AREMAP>
; __device__ __forceinline__ void gemm_phase(LAS unsigned char* lds, const Gemm g, const Sched& S, const Epi& E, int wv) {
;     ...
;             PG8_LDB(B0, 0, 0); PG8_SCHED; PG8_LDA(At, 0, 0); PG8_STAGE(PG8_SA(1, 1), a1 + hstepA, voffA);
;             PG8_WAIT_L(8); PG8_BAR; PG8_WAIT_L(0); PG8_MMA(0, 0, At, B0); PG8_BAR; PG8_SCHED;
;             PG8_LDB(B1, 0, 1); PG8_STAGE(PG8_SB(0, 0), b2, voffB);
;             PG8_BAR; PG8_WAIT_L(0); PG8_MMA(0, 1, At, B1); PG8_BAR;
;             PG8_LDA(At, 0, 1); PG8_STAGE(PG8_SA(0, 0), a2, voffA);
;             PG8_BAR; PG8_WAIT_L(0); PG8_MMA(1, 0, At, B0); PG8_BAR; PG8_SCHED;
;             PG8_STAGE(PG8_SB(0, 1), b2 + hstepB, voffB);
;             PG8_WAIT_V(6); PG8_BAR; PG8_MMA(1, 1, At, B1); PG8_BAR;
.LBB0_552:
	s_add_u32 s34, s2, 0x100
	s_addc_u32 s35, s3, 0
	s_add_i32 s38, 0, 0x10000
	v_add_u32_e32 v1, s38, v250
	ds_read_b128 v[130:133], v1
	ds_read_b128 v[134:137], v1 offset:1024
	ds_read_b128 v[138:141], v1 offset:2048
	ds_read_b128 v[142:145], v1 offset:3072
	s_cmp_eq_u32 s76, 28
	s_cselect_b32 s67, s23, s35
	s_cselect_b32 s66, s72, s34
	s_cselect_b32 s63, s21, s75
	s_cselect_b32 s62, s73, s74
	s_add_i32 m0, s29, 0xc000
	ds_read_b128 v[146:149], v252
	ds_read_b128 v[150:153], v252 offset:1024
	ds_read_b128 v[154:157], v252 offset:2048
	ds_read_b128 v[158:161], v252 offset:3072
	ds_read_b128 v[162:165], v252 offset:4096
	ds_read_b128 v[166:169], v252 offset:5120
	ds_read_b128 v[170:173], v252 offset:6144
	ds_read_b128 v[174:177], v252 offset:7168
	global_load_lds_dwordx4 v202, s[2:3]
	s_add_i32 m0, s29, 0xe000
	s_nop 0
	global_load_lds_dwordx4 v200, s[2:3]
	s_waitcnt lgkmcnt(8)
	s_barrier
	s_waitcnt lgkmcnt(0)
	s_waitcnt lgkmcnt(0)
	v_mfma_f32_16x16x32_bf16 v[126:129], v[130:133], v[146:149], v[126:129]
	v_mfma_f32_16x16x32_bf16 v[110:113], v[138:141], v[146:149], v[110:113]
	v_mfma_f32_16x16x32_bf16 v[122:125], v[130:133], v[154:157], v[122:125]
	v_mfma_f32_16x16x32_bf16 v[106:109], v[138:141], v[154:157], v[106:109]
	v_mfma_f32_16x16x32_bf16 v[118:121], v[130:133], v[162:165], v[118:121]
	v_mfma_f32_16x16x32_bf16 v[102:105], v[138:141], v[162:165], v[102:105]
	v_mfma_f32_16x16x32_bf16 v[114:117], v[130:133], v[170:173], v[114:117]
	v_mfma_f32_16x16x32_bf16 v[98:101], v[138:141], v[170:173], v[98:101]
	v_mfma_f32_16x16x32_bf16 v[126:129], v[134:137], v[150:153], v[126:129]
	v_mfma_f32_16x16x32_bf16 v[110:113], v[142:145], v[150:153], v[110:113]
	v_mfma_f32_16x16x32_bf16 v[122:125], v[134:137], v[158:161], v[122:125]
	v_mfma_f32_16x16x32_bf16 v[106:109], v[142:145], v[158:161], v[106:109]
	v_mfma_f32_16x16x32_bf16 v[118:121], v[134:137], v[166:169], v[118:121]
	v_mfma_f32_16x16x32_bf16 v[102:105], v[142:145], v[166:169], v[102:105]
	v_mfma_f32_16x16x32_bf16 v[114:117], v[134:137], v[174:177], v[114:117]
	v_mfma_f32_16x16x32_bf16 v[98:101], v[142:145], v[174:177], v[98:101]
	s_barrier
	s_add_i32 s39, 0, 0x14000
	s_add_i32 s2, s38, s53
	v_add_u32_e32 v1, s39, v250
	s_add_u32 s80, s62, 0x80
	s_addc_u32 s81, s63, 0
	s_mov_b32 m0, s2
	ds_read_b128 v[178:181], v1
	ds_read_b128 v[182:185], v1 offset:1024
	ds_read_b128 v[192:195], v1 offset:2048
	ds_read_b128 v[204:207], v1 offset:3072
	global_load_lds_dwordx4 v196, s[62:63]
	s_add_i32 m0, s2, 0x2000
	s_nop 0
	global_load_lds_dwordx4 v198, s[62:63]
	s_barrier
	s_waitcnt lgkmcnt(0)
	s_waitcnt lgkmcnt(0)
	v_mfma_f32_16x16x32_bf16 v[94:97], v[178:181], v[146:149], v[94:97]
	v_mfma_f32_16x16x32_bf16 v[78:81], v[192:195], v[146:149], v[78:81]
	v_mfma_f32_16x16x32_bf16 v[90:93], v[178:181], v[154:157], v[90:93]
	v_mfma_f32_16x16x32_bf16 v[74:77], v[192:195], v[154:157], v[74:77]
	v_mfma_f32_16x16x32_bf16 v[86:89], v[178:181], v[162:165], v[86:89]
	v_mfma_f32_16x16x32_bf16 v[70:73], v[192:195], v[162:165], v[70:73]
	v_mfma_f32_16x16x32_bf16 v[82:85], v[178:181], v[170:173], v[82:85]
	v_mfma_f32_16x16x32_bf16 v[66:69], v[192:195], v[170:173], v[66:69]
	v_mfma_f32_16x16x32_bf16 v[94:97], v[182:185], v[150:153], v[94:97]
	v_mfma_f32_16x16x32_bf16 v[78:81], v[204:207], v[150:153], v[78:81]
	v_mfma_f32_16x16x32_bf16 v[90:93], v[182:185], v[158:161], v[90:93]
	v_mfma_f32_16x16x32_bf16 v[74:77], v[204:207], v[158:161], v[74:77]
	v_mfma_f32_16x16x32_bf16 v[86:89], v[182:185], v[166:169], v[86:89]
	v_mfma_f32_16x16x32_bf16 v[70:73], v[204:207], v[166:169], v[70:73]
	v_mfma_f32_16x16x32_bf16 v[82:85], v[182:185], v[174:177], v[82:85]
	v_mfma_f32_16x16x32_bf16 v[66:69], v[204:207], v[174:177], v[66:69]
	s_mov_b32 m0, s29
	s_add_u32 s96, s66, 0x80
	s_addc_u32 s97, s67, 0
	s_barrier
	ds_read_b128 v[146:149], v252 offset:16384
	ds_read_b128 v[150:153], v252 offset:17408
	ds_read_b128 v[154:157], v252 offset:18432
	ds_read_b128 v[158:161], v252 offset:19456
	ds_read_b128 v[162:165], v252 offset:20480
	ds_read_b128 v[166:169], v252 offset:21504
	ds_read_b128 v[170:173], v252 offset:22528
	ds_read_b128 v[174:177], v252 offset:23552
	global_load_lds_dwordx4 v196, s[66:67]
	s_mov_b32 m0, s31
	s_nop 0
	global_load_lds_dwordx4 v198, s[66:67]
	s_barrier
	s_waitcnt lgkmcnt(0)
	s_waitcnt lgkmcnt(0)
	v_mfma_f32_16x16x32_bf16 v[62:65], v[130:133], v[146:149], v[62:65]
	v_mfma_f32_16x16x32_bf16 v[46:49], v[138:141], v[146:149], v[46:49]
	v_mfma_f32_16x16x32_bf16 v[58:61], v[130:133], v[154:157], v[58:61]
	v_mfma_f32_16x16x32_bf16 v[42:45], v[138:141], v[154:157], v[42:45]
	v_mfma_f32_16x16x32_bf16 v[54:57], v[130:133], v[162:165], v[54:57]
	v_mfma_f32_16x16x32_bf16 v[38:41], v[138:141], v[162:165], v[38:41]
	v_mfma_f32_16x16x32_bf16 v[50:53], v[130:133], v[170:173], v[50:53]
	v_mfma_f32_16x16x32_bf16 v[34:37], v[138:141], v[170:173], v[34:37]
	v_mfma_f32_16x16x32_bf16 v[62:65], v[134:137], v[150:153], v[62:65]
	v_mfma_f32_16x16x32_bf16 v[46:49], v[142:145], v[150:153], v[46:49]
	v_mfma_f32_16x16x32_bf16 v[58:61], v[134:137], v[158:161], v[58:61]
	v_mfma_f32_16x16x32_bf16 v[42:45], v[142:145], v[158:161], v[42:45]
	v_mfma_f32_16x16x32_bf16 v[54:57], v[134:137], v[166:169], v[54:57]
	v_mfma_f32_16x16x32_bf16 v[38:41], v[142:145], v[166:169], v[38:41]
	v_mfma_f32_16x16x32_bf16 v[50:53], v[134:137], v[174:177], v[50:53]
	v_mfma_f32_16x16x32_bf16 v[34:37], v[142:145], v[174:177], v[34:37]
	s_barrier
	s_add_u32 s2, s62, 0x80000
	s_addc_u32 s3, s63, 0
	s_add_i32 s38, s39, s53
	s_mov_b32 m0, s38
	s_nop 0
	global_load_lds_dwordx4 v196, s[2:3]
	s_add_i32 m0, s38, 0x2000
	s_nop 0
	global_load_lds_dwordx4 v198, s[2:3]
	s_waitcnt vmcnt(6)
	s_barrier
; #define PG8_STAGE(bufoff, gbase, voff) do { _Pragma("unroll") for (int _i = 0; _i < 2; ++_i) \
;         __builtin_amdgcn_global_load_lds((const unsigned*)((const char*)(gbase) + (voff)[_i]), (LAS unsigned*)(lds + (bufoff) + ldsw + _i * 8192), 16, 0, 0); } while (0)
; #define PG8_LDA(dst, b, h) do { _Pragma("unroll") for (int m = 0; m < 4; ++m) _Pragma("unroll") for (int k = 0; k < 2; ++k) dst[m][k] = *(const LAS bf16x8*)(lds + PG8_SA(b, h) + aoff + m * 2048 + k * 1024); } while (0)
; #define PG8_LDB(dst, b, h) do { _Pragma("unroll") for (int n = 0; n < 2; ++n) _Pragma("unroll") for (int k = 0; k < 2; ++k) dst[n][k] = *(const LAS bf16x8*)(lds + PG8_SB(b, h) + boff + n * 2048 + k * 1024); } while (0)
; #define PG8_MMA(ai, bj, At, Bt) do { __builtin_amdgcn_s_setprio(1); _Pragma("unroll") for (int m = 0; m < 4; ++m) _Pragma("unroll") for (int n = 0; n < 2; ++n) _Pragma("unroll") for (int k = 0; k < 2; ++k) \
;         acc[ai][bj][m][n] = __builtin_amdgcn_mfma_f32_16x16x32_bf16(Bt[n][k], At[m][k], acc[ai][bj][m][n], 0, 0, 0); __builtin_amdgcn_s_setprio(0); } while (0)
; #define PG8_WAIT_V(n) asm volatile("s_waitcnt vmcnt(" #n ")" ::: "memory")
; #define PG8_WAIT_L(n) asm volatile("s_waitcnt lgkmcnt(" #n ")" ::: "memory")
; #define PG8_BAR __builtin_amdgcn_s_barrier()
; #define PG8_SCHED __builtin_amdgcn_sched_barrier(0)
; template <class Epi, class Sched, bool AREMAP>
; __device__ __forceinline__ void gemm_phase(LAS unsigned char* lds, const Gemm g, const Sched& S, const Epi& E, int wv) {
;     ...
;             PG8_STAGE(PG8_SB(0, 1), b2 + hstepB, voffB);
;             PG8_WAIT_V(6); PG8_BAR; PG8_MMA(1, 1, At, B1); PG8_BAR;
;             PG8_LDB(B0, 1, 0); PG8_SCHED; PG8_LDA(At, 1, 0); PG8_STAGE(PG8_SA(0, 1), a2 + hstepA, voffA);
;             PG8_WAIT_L(8); PG8_BAR; PG8_WAIT_L(0); PG8_MMA(0, 0, At, B0); PG8_BAR; PG8_SCHED;
;             PG8_LDB(B1, 1, 1); PG8_STAGE(PG8_SB(1, 0), b3, voffB);
;             PG8_BAR; PG8_WAIT_L(0); PG8_MMA(0, 1, At, B1); PG8_BAR;
	v_mfma_f32_16x16x32_bf16 v[30:33], v[178:181], v[146:149], v[30:33]
	v_mfma_f32_16x16x32_bf16 v[14:17], v[192:195], v[146:149], v[14:17]
	v_mfma_f32_16x16x32_bf16 v[26:29], v[178:181], v[154:157], v[26:29]
	v_mfma_f32_16x16x32_bf16 v[10:13], v[192:195], v[154:157], v[10:13]
	v_mfma_f32_16x16x32_bf16 v[22:25], v[178:181], v[162:165], v[22:25]
	v_mfma_f32_16x16x32_bf16 v[6:9], v[192:195], v[162:165], v[6:9]
	v_mfma_f32_16x16x32_bf16 v[18:21], v[178:181], v[170:173], v[18:21]
	v_mfma_f32_16x16x32_bf16 v[2:5], v[192:195], v[170:173], v[2:5]
	v_mfma_f32_16x16x32_bf16 v[30:33], v[182:185], v[150:153], v[30:33]
	v_mfma_f32_16x16x32_bf16 v[14:17], v[204:207], v[150:153], v[14:17]
	v_mfma_f32_16x16x32_bf16 v[26:29], v[182:185], v[158:161], v[26:29]
	v_mfma_f32_16x16x32_bf16 v[10:13], v[204:207], v[158:161], v[10:13]
	v_mfma_f32_16x16x32_bf16 v[22:25], v[182:185], v[166:169], v[22:25]
	v_mfma_f32_16x16x32_bf16 v[6:9], v[204:207], v[166:169], v[6:9]
	v_mfma_f32_16x16x32_bf16 v[18:21], v[182:185], v[174:177], v[18:21]
	v_mfma_f32_16x16x32_bf16 v[2:5], v[204:207], v[174:177], v[2:5]
	s_add_i32 s38, 0, 0x18000
	v_add_u32_e32 v1, s38, v250
	s_barrier
	ds_read_b128 v[130:133], v1
	ds_read_b128 v[134:137], v1 offset:1024
	ds_read_b128 v[138:141], v1 offset:2048
	ds_read_b128 v[142:145], v1 offset:3072
	s_add_u32 s2, s66, 0x80000
	s_addc_u32 s3, s67, 0
	s_mov_b32 m0, s55
	ds_read_b128 v[146:149], v252 offset:32768
	ds_read_b128 v[150:153], v252 offset:33792
	ds_read_b128 v[154:157], v252 offset:34816
	ds_read_b128 v[158:161], v252 offset:35840
	ds_read_b128 v[162:165], v252 offset:36864
	ds_read_b128 v[166:169], v252 offset:37888
	ds_read_b128 v[170:173], v252 offset:38912
	ds_read_b128 v[174:177], v252 offset:39936
	global_load_lds_dwordx4 v196, s[2:3]
	s_mov_b32 m0, s56
	s_nop 0
	global_load_lds_dwordx4 v198, s[2:3]
	s_waitcnt lgkmcnt(8)
	s_barrier
	s_waitcnt lgkmcnt(0)
	s_waitcnt lgkmcnt(0)
	v_mfma_f32_16x16x32_bf16 v[126:129], v[130:133], v[146:149], v[126:129]
	v_mfma_f32_16x16x32_bf16 v[110:113], v[138:141], v[146:149], v[110:113]
	v_mfma_f32_16x16x32_bf16 v[122:125], v[130:133], v[154:157], v[122:125]
	v_mfma_f32_16x16x32_bf16 v[106:109], v[138:141], v[154:157], v[106:109]
	v_mfma_f32_16x16x32_bf16 v[118:121], v[130:133], v[162:165], v[118:121]
	v_mfma_f32_16x16x32_bf16 v[102:105], v[138:141], v[162:165], v[102:105]
	v_mfma_f32_16x16x32_bf16 v[114:117], v[130:133], v[170:173], v[114:117]
	v_mfma_f32_16x16x32_bf16 v[98:101], v[138:141], v[170:173], v[98:101]
	v_mfma_f32_16x16x32_bf16 v[126:129], v[134:137], v[150:153], v[126:129]
	v_mfma_f32_16x16x32_bf16 v[110:113], v[142:145], v[150:153], v[110:113]
	v_mfma_f32_16x16x32_bf16 v[122:125], v[134:137], v[158:161], v[122:125]
	v_mfma_f32_16x16x32_bf16 v[106:109], v[142:145], v[158:161], v[106:109]
	v_mfma_f32_16x16x32_bf16 v[118:121], v[134:137], v[166:169], v[118:121]
	v_mfma_f32_16x16x32_bf16 v[102:105], v[142:145], v[166:169], v[102:105]
	v_mfma_f32_16x16x32_bf16 v[114:117], v[134:137], v[174:177], v[114:117]
	v_mfma_f32_16x16x32_bf16 v[98:101], v[142:145], v[174:177], v[98:101]
	s_barrier
	s_add_i32 s39, 0, 0x1c000
	s_add_i32 s2, s38, s53
	v_add_u32_e32 v1, s39, v250
	s_mov_b32 m0, s2
	ds_read_b128 v[178:181], v1
	ds_read_b128 v[182:185], v1 offset:1024
	ds_read_b128 v[192:195], v1 offset:2048
	ds_read_b128 v[204:207], v1 offset:3072
	global_load_lds_dwordx4 v196, s[80:81]
	s_add_i32 m0, s2, 0x2000
	s_nop 0
	global_load_lds_dwordx4 v198, s[80:81]
	s_barrier
	s_waitcnt lgkmcnt(0)
	s_waitcnt lgkmcnt(0)
	v_mfma_f32_16x16x32_bf16 v[94:97], v[178:181], v[146:149], v[94:97]
	v_mfma_f32_16x16x32_bf16 v[78:81], v[192:195], v[146:149], v[78:81]
	v_mfma_f32_16x16x32_bf16 v[90:93], v[178:181], v[154:157], v[90:93]
	v_mfma_f32_16x16x32_bf16 v[74:77], v[192:195], v[154:157], v[74:77]
	v_mfma_f32_16x16x32_bf16 v[86:89], v[178:181], v[162:165], v[86:89]
	v_mfma_f32_16x16x32_bf16 v[70:73], v[192:195], v[162:165], v[70:73]
	v_mfma_f32_16x16x32_bf16 v[82:85], v[178:181], v[170:173], v[82:85]
	v_mfma_f32_16x16x32_bf16 v[66:69], v[192:195], v[170:173], v[66:69]
	v_mfma_f32_16x16x32_bf16 v[94:97], v[182:185], v[150:153], v[94:97]
	v_mfma_f32_16x16x32_bf16 v[78:81], v[204:207], v[150:153], v[78:81]
	v_mfma_f32_16x16x32_bf16 v[90:93], v[182:185], v[158:161], v[90:93]
	v_mfma_f32_16x16x32_bf16 v[74:77], v[204:207], v[158:161], v[74:77]
	v_mfma_f32_16x16x32_bf16 v[86:89], v[182:185], v[166:169], v[86:89]
	v_mfma_f32_16x16x32_bf16 v[70:73], v[204:207], v[166:169], v[70:73]
	v_mfma_f32_16x16x32_bf16 v[82:85], v[182:185], v[174:177], v[82:85]
	v_mfma_f32_16x16x32_bf16 v[66:69], v[204:207], v[174:177], v[66:69]
	s_mov_b32 m0, s57
	s_barrier
; #define PG8_STAGE(bufoff, gbase, voff) do { _Pragma("unroll") for (int _i = 0; _i < 2; ++_i) \
;         __builtin_amdgcn_global_load_lds((const unsigned*)((const char*)(gbase) + (voff)[_i]), (LAS unsigned*)(lds + (bufoff) + ldsw + _i * 8192), 16, 0, 0); } while (0)
; #define PG8_LDA(dst, b, h) do { _Pragma("unroll") for (int m = 0; m < 4; ++m) _Pragma("unroll") for (int k = 0; k < 2; ++k) dst[m][k] = *(const LAS bf16x8*)(lds + PG8_SA(b, h) + aoff + m * 2048 + k * 1024); } while (0)
; #define PG8_MMA(ai, bj, At, Bt) do { __builtin_amdgcn_s_setprio(1); _Pragma("unroll") for (int m = 0; m < 4; ++m) _Pragma("unroll") for (int n = 0; n < 2; ++n) _Pragma("unroll") for (int k = 0; k < 2; ++k) \
;         acc[ai][bj][m][n] = __builtin_amdgcn_mfma_f32_16x16x32_bf16(Bt[n][k], At[m][k], acc[ai][bj][m][n], 0, 0, 0); __builtin_amdgcn_s_setprio(0); } while (0)
; #define PG8_WAIT_V(n) asm volatile("s_waitcnt vmcnt(" #n ")" ::: "memory")
; #define PG8_WAIT_L(n) asm volatile("s_waitcnt lgkmcnt(" #n ")" ::: "memory")
; #define PG8_BAR __builtin_amdgcn_s_barrier()
; #define PG8_SCHED __builtin_amdgcn_sched_barrier(0)
; template <class Epi, class Sched, bool AREMAP>
; __device__ __forceinline__ void gemm_phase(LAS unsigned char* lds, const Gemm g, const Sched& S, const Epi& E, int wv) {
;     ...
;             PG8_LDA(At, 1, 1); PG8_STAGE(PG8_SA(1, 0), a3, voffA);
;             PG8_BAR; PG8_WAIT_L(0); PG8_MMA(1, 0, At, B0); PG8_BAR; PG8_SCHED;
;             PG8_STAGE(PG8_SB(1, 1), b3 + hstepB, voffB);
;             PG8_WAIT_V(6); PG8_BAR; PG8_MMA(1, 1, At, B1); PG8_BAR;
;         }
;         E(acc, cur, wr, wc, fr, fq);
;     __device__ __forceinline__ void operator()(const f32x4 (&acc)[2][2][4][2], const Unit& u, int wr, int wc, int fr, int fq) const {
;         const int row0 = u.pm * BM + wr * 64 + fr, col0 = u.pn * BM + wc * 32 + 4 * fq;
;         const float* gv = gate + (size_t)(u.pm >> 3) * 12288 + col0;
; #pragma unroll
;         for (int ai = 0; ai < 2; ++ai) {
;             float mu[4], rs[4];
; #pragma unroll
;             for (int m = 0; m < 4; ++m) { mu[m] = 0.f; rs[m] = 1.f;
;                 if (stats) { const float* sp = stats + (size_t)(row0 + ai * HALF + m * 16) * 2; mu[m] = sp[0]; rs[m] = sp[1]; } }
	ds_read_b128 v[146:149], v252 offset:49152
	ds_read_b128 v[150:153], v252 offset:50176
	ds_read_b128 v[154:157], v252 offset:51200
	ds_read_b128 v[158:161], v252 offset:52224
	ds_read_b128 v[162:165], v252 offset:53248
	ds_read_b128 v[166:169], v252 offset:54272
	ds_read_b128 v[170:173], v252 offset:55296
	ds_read_b128 v[174:177], v252 offset:56320
	global_load_lds_dwordx4 v196, s[96:97]
	s_mov_b32 m0, s65
	s_nop 0
	global_load_lds_dwordx4 v198, s[96:97]
	s_barrier
	s_waitcnt lgkmcnt(0)
	s_waitcnt lgkmcnt(0)
	v_mfma_f32_16x16x32_bf16 v[62:65], v[130:133], v[146:149], v[62:65]
	v_mfma_f32_16x16x32_bf16 v[46:49], v[138:141], v[146:149], v[46:49]
	v_mfma_f32_16x16x32_bf16 v[58:61], v[130:133], v[154:157], v[58:61]
	v_mfma_f32_16x16x32_bf16 v[42:45], v[138:141], v[154:157], v[42:45]
	v_mfma_f32_16x16x32_bf16 v[54:57], v[130:133], v[162:165], v[54:57]
	v_mfma_f32_16x16x32_bf16 v[38:41], v[138:141], v[162:165], v[38:41]
	v_mfma_f32_16x16x32_bf16 v[50:53], v[130:133], v[170:173], v[50:53]
	v_mfma_f32_16x16x32_bf16 v[34:37], v[138:141], v[170:173], v[34:37]
	v_mfma_f32_16x16x32_bf16 v[62:65], v[134:137], v[150:153], v[62:65]
	v_mfma_f32_16x16x32_bf16 v[46:49], v[142:145], v[150:153], v[46:49]
	v_mfma_f32_16x16x32_bf16 v[58:61], v[134:137], v[158:161], v[58:61]
	v_mfma_f32_16x16x32_bf16 v[42:45], v[142:145], v[158:161], v[42:45]
	v_mfma_f32_16x16x32_bf16 v[54:57], v[134:137], v[166:169], v[54:57]
	v_mfma_f32_16x16x32_bf16 v[38:41], v[142:145], v[166:169], v[38:41]
	v_mfma_f32_16x16x32_bf16 v[50:53], v[134:137], v[174:177], v[50:53]
	v_mfma_f32_16x16x32_bf16 v[34:37], v[142:145], v[174:177], v[34:37]
	s_barrier
	s_add_u32 s2, s62, 0x80080
	s_addc_u32 s3, s63, 0
	s_add_i32 s38, s39, s53
	s_mov_b32 m0, s38
	s_nop 0
	global_load_lds_dwordx4 v196, s[2:3]
	s_add_i32 m0, s38, 0x2000
	s_nop 0
	global_load_lds_dwordx4 v198, s[2:3]
	s_waitcnt vmcnt(6)
	s_barrier
	v_mfma_f32_16x16x32_bf16 v[30:33], v[178:181], v[146:149], v[30:33]
	v_mfma_f32_16x16x32_bf16 v[14:17], v[192:195], v[146:149], v[14:17]
	v_mfma_f32_16x16x32_bf16 v[26:29], v[178:181], v[154:157], v[26:29]
	v_mfma_f32_16x16x32_bf16 v[10:13], v[192:195], v[154:157], v[10:13]
	v_mfma_f32_16x16x32_bf16 v[22:25], v[178:181], v[162:165], v[22:25]
	v_mfma_f32_16x16x32_bf16 v[6:9], v[192:195], v[162:165], v[6:9]
	v_mfma_f32_16x16x32_bf16 v[18:21], v[178:181], v[170:173], v[18:21]
	v_mfma_f32_16x16x32_bf16 v[2:5], v[192:195], v[170:173], v[2:5]
	v_mfma_f32_16x16x32_bf16 v[30:33], v[182:185], v[150:153], v[30:33]
	v_mfma_f32_16x16x32_bf16 v[14:17], v[204:207], v[150:153], v[14:17]
	v_mfma_f32_16x16x32_bf16 v[26:29], v[182:185], v[158:161], v[26:29]
	v_mfma_f32_16x16x32_bf16 v[10:13], v[204:207], v[158:161], v[10:13]
	v_mfma_f32_16x16x32_bf16 v[22:25], v[182:185], v[166:169], v[22:25]
	v_mfma_f32_16x16x32_bf16 v[6:9], v[204:207], v[166:169], v[6:9]
	v_mfma_f32_16x16x32_bf16 v[18:21], v[182:185], v[174:177], v[18:21]
	v_mfma_f32_16x16x32_bf16 v[2:5], v[204:207], v[174:177], v[2:5]
	s_add_i32 s76, s76, 2
	s_add_u32 s74, s74, 0x100
	s_addc_u32 s75, s75, 0
	s_cmp_gt_u32 s76, 29
	s_mov_b64 s[2:3], s[34:35]
	s_barrier
	s_cbranch_scc0 .LBB0_552
	v_lshl_add_u32 v212, s28, 8, v249
	v_cndmask_b32_e64 v1, 0, 1, s[18:19]
	v_mov_b32_e32 v216, 1.0
	v_cmp_ne_u32_e64 s[2:3], 1, v1
	s_andn2_b64 vcc, exec, s[18:19]
	v_ashrrev_i32_e32 v213, 31, v212
	s_cbranch_vccnz .LBB0_556
	v_lshl_add_u64 v[130:131], v[212:213], 3, s[12:13]
	global_load_dwordx2 v[134:135], v[130:131], off
	v_or_b32_e32 v140, 16, v212
	s_and_b64 vcc, exec, s[2:3]
	v_ashrrev_i32_e32 v141, 31, v140
	s_cbranch_vccnz .LBB0_557

; #define PG8_STAGE(bufoff, gbase, voff) do { _Pragma("unroll") for (int _i = 0; _i < 2; ++_i) \
;         __builtin_amdgcn_global_load_lds((const unsigned*)((const char*)(gbase) + (voff)[_i]), (LAS unsigned*)(lds + (bufoff) + ldsw + _i * 8192), 16, 0, 0); } while (0)
; #define PG8_LDA(dst, b, h) do { _Pragma("unroll") for (int m = 0; m < 4; ++m) _Pragma("unroll") for (int k = 0; k < 2; ++k) dst[m][k] = *(const LAS bf16x8*)(lds + PG8_SA(b, h) + aoff + m * 2048 + k * 1024); } while (0)
; #define PG8_LDB(dst, b, h) do { _Pragma("unroll") for (int n = 0; n < 2; ++n) _Pragma("unroll") for (int k = 0; k < 2; ++k) dst[n][k] = *(const LAS bf16x8*)(lds + PG8_SB(b, h) + boff + n * 2048 + k * 1024); } while (0)
; #define PG8_MMA(ai, bj, At, Bt) do { __builtin_amdgcn_s_setprio(1); _Pragma("unroll") for (int m = 0; m < 4; ++m) _Pragma("unroll") for (int n = 0; n < 2; ++n) _Pragma("unroll") for (int k = 0; k < 2; ++k) \
;         acc[ai][bj][m][n] = __builtin_amdgcn_mfma_f32_16x16x32_bf16(Bt[n][k], At[m][k], acc[ai][bj][m][n], 0, 0, 0); __builtin_amdgcn_s_setprio(0); } while (0)
; #define PG8_WAIT_V(n) asm volatile("s_waitcnt vmcnt(" #n ")" ::: "memory")
; #define PG8_WAIT_L(n) asm volatile("s_waitcnt lgkmcnt(" #n ")" ::: "memory")
; #define PG8_BAR __builtin_amdgcn_s_barrier()
; #define PG8_SCHED __builtin_amdgcn_sched_barrier(0)
; template <class Epi, class Sched, bool AREMAP>
; __device__ __forceinline__ void gemm_phase(LAS unsigned char* lds, const Gemm g, const Sched& S, const Epi& E, int wv) {
;     ...
;             PG8_LDB(B0, 0, 0); PG8_SCHED; PG8_LDA(At, 0, 0); PG8_STAGE(PG8_SA(1, 1), a1 + hstepA, voffA);
;             PG8_WAIT_L(8); PG8_BAR; PG8_WAIT_L(0); PG8_MMA(0, 0, At, B0); PG8_BAR; PG8_SCHED;
;             PG8_LDB(B1, 0, 1); PG8_STAGE(PG8_SB(0, 0), b2, voffB);
;             PG8_BAR; PG8_WAIT_L(0); PG8_MMA(0, 1, At, B1); PG8_BAR;
;             PG8_LDA(At, 0, 1); PG8_STAGE(PG8_SA(0, 0), a2, voffA);
;             PG8_BAR; PG8_WAIT_L(0); PG8_MMA(1, 0, At, B0); PG8_BAR; PG8_SCHED;
;             PG8_STAGE(PG8_SB(0, 1), b2 + hstepB, voffB);
;             PG8_WAIT_V(6); PG8_BAR; PG8_MMA(1, 1, At, B1); PG8_BAR;
.LBB0_674:
	s_add_u32 s2, s24, 0x100
	s_addc_u32 s3, s25, 0
	s_add_i32 s33, 0, 0x10000
	v_add_u32_e32 v1, s33, v250
	ds_read_b128 v[130:133], v1
	ds_read_b128 v[134:137], v1 offset:1024
	ds_read_b128 v[138:141], v1 offset:2048
	ds_read_b128 v[142:145], v1 offset:3072
	s_cmpk_eq_i32 s67, 0x54
	s_cselect_b32 s29, s23, s3
	s_cselect_b32 s28, s22, s2
	s_cselect_b32 s27, s5, s66
	s_cselect_b32 s26, s4, s65
	s_add_i32 m0, s35, 0xc000
	ds_read_b128 v[146:149], v252
	ds_read_b128 v[150:153], v252 offset:1024
	ds_read_b128 v[154:157], v252 offset:2048
	ds_read_b128 v[158:161], v252 offset:3072
	ds_read_b128 v[162:165], v252 offset:4096
	ds_read_b128 v[166:169], v252 offset:5120
	ds_read_b128 v[170:173], v252 offset:6144
	ds_read_b128 v[174:177], v252 offset:7168
	global_load_lds_dwordx4 v202, s[24:25]
	s_add_i32 m0, s35, 0xe000
	s_nop 0
	global_load_lds_dwordx4 v200, s[24:25]
	s_waitcnt lgkmcnt(8)
	s_barrier
	s_waitcnt lgkmcnt(0)
	s_waitcnt lgkmcnt(0)
	v_mfma_f32_16x16x32_bf16 v[126:129], v[130:133], v[146:149], v[126:129]
	v_mfma_f32_16x16x32_bf16 v[110:113], v[138:141], v[146:149], v[110:113]
	v_mfma_f32_16x16x32_bf16 v[122:125], v[130:133], v[154:157], v[122:125]
	v_mfma_f32_16x16x32_bf16 v[106:109], v[138:141], v[154:157], v[106:109]
	v_mfma_f32_16x16x32_bf16 v[118:121], v[130:133], v[162:165], v[118:121]
	v_mfma_f32_16x16x32_bf16 v[102:105], v[138:141], v[162:165], v[102:105]
	v_mfma_f32_16x16x32_bf16 v[114:117], v[130:133], v[170:173], v[114:117]
	v_mfma_f32_16x16x32_bf16 v[98:101], v[138:141], v[170:173], v[98:101]
	v_mfma_f32_16x16x32_bf16 v[126:129], v[134:137], v[150:153], v[126:129]
	v_mfma_f32_16x16x32_bf16 v[110:113], v[142:145], v[150:153], v[110:113]
	v_mfma_f32_16x16x32_bf16 v[122:125], v[134:137], v[158:161], v[122:125]
	v_mfma_f32_16x16x32_bf16 v[106:109], v[142:145], v[158:161], v[106:109]
	v_mfma_f32_16x16x32_bf16 v[118:121], v[134:137], v[166:169], v[118:121]
	v_mfma_f32_16x16x32_bf16 v[102:105], v[142:145], v[166:169], v[102:105]
	v_mfma_f32_16x16x32_bf16 v[114:117], v[134:137], v[174:177], v[114:117]
	v_mfma_f32_16x16x32_bf16 v[98:101], v[142:145], v[174:177], v[98:101]
	s_barrier
	s_add_i32 s38, 0, 0x14000
	s_add_i32 s24, s33, s34
	v_add_u32_e32 v1, s38, v250
	s_add_u32 s80, s26, 0x80
	s_addc_u32 s81, s27, 0
	s_mov_b32 m0, s24
	ds_read_b128 v[178:181], v1
	ds_read_b128 v[182:185], v1 offset:1024
	ds_read_b128 v[192:195], v1 offset:2048
	ds_read_b128 v[204:207], v1 offset:3072
	global_load_lds_dwordx4 v196, s[26:27]
	s_add_i32 m0, s24, 0x2000
	s_nop 0
	global_load_lds_dwordx4 v198, s[26:27]
	s_barrier
	s_waitcnt lgkmcnt(0)
	s_waitcnt lgkmcnt(0)
	v_mfma_f32_16x16x32_bf16 v[94:97], v[178:181], v[146:149], v[94:97]
	v_mfma_f32_16x16x32_bf16 v[78:81], v[192:195], v[146:149], v[78:81]
	v_mfma_f32_16x16x32_bf16 v[90:93], v[178:181], v[154:157], v[90:93]
	v_mfma_f32_16x16x32_bf16 v[74:77], v[192:195], v[154:157], v[74:77]
	v_mfma_f32_16x16x32_bf16 v[86:89], v[178:181], v[162:165], v[86:89]
	v_mfma_f32_16x16x32_bf16 v[70:73], v[192:195], v[162:165], v[70:73]
	v_mfma_f32_16x16x32_bf16 v[82:85], v[178:181], v[170:173], v[82:85]
	v_mfma_f32_16x16x32_bf16 v[66:69], v[192:195], v[170:173], v[66:69]
	v_mfma_f32_16x16x32_bf16 v[94:97], v[182:185], v[150:153], v[94:97]
	v_mfma_f32_16x16x32_bf16 v[78:81], v[204:207], v[150:153], v[78:81]
	v_mfma_f32_16x16x32_bf16 v[90:93], v[182:185], v[158:161], v[90:93]
	v_mfma_f32_16x16x32_bf16 v[74:77], v[204:207], v[158:161], v[74:77]
	v_mfma_f32_16x16x32_bf16 v[86:89], v[182:185], v[166:169], v[86:89]
	v_mfma_f32_16x16x32_bf16 v[70:73], v[204:207], v[166:169], v[70:73]
	v_mfma_f32_16x16x32_bf16 v[82:85], v[182:185], v[174:177], v[82:85]
	v_mfma_f32_16x16x32_bf16 v[66:69], v[204:207], v[174:177], v[66:69]
	s_mov_b32 m0, s35
	s_add_u32 s96, s28, 0x80
	s_addc_u32 s97, s29, 0
	s_barrier
	ds_read_b128 v[146:149], v252 offset:16384
	ds_read_b128 v[150:153], v252 offset:17408
	ds_read_b128 v[154:157], v252 offset:18432
	ds_read_b128 v[158:161], v252 offset:19456
	ds_read_b128 v[162:165], v252 offset:20480
	ds_read_b128 v[166:169], v252 offset:21504
	ds_read_b128 v[170:173], v252 offset:22528
	ds_read_b128 v[174:177], v252 offset:23552
	global_load_lds_dwordx4 v196, s[28:29]
	s_mov_b32 m0, s36
	s_nop 0
	global_load_lds_dwordx4 v198, s[28:29]
	s_barrier
	s_waitcnt lgkmcnt(0)
	s_waitcnt lgkmcnt(0)
	v_mfma_f32_16x16x32_bf16 v[62:65], v[130:133], v[146:149], v[62:65]
	v_mfma_f32_16x16x32_bf16 v[46:49], v[138:141], v[146:149], v[46:49]
	v_mfma_f32_16x16x32_bf16 v[58:61], v[130:133], v[154:157], v[58:61]
	v_mfma_f32_16x16x32_bf16 v[42:45], v[138:141], v[154:157], v[42:45]
	v_mfma_f32_16x16x32_bf16 v[54:57], v[130:133], v[162:165], v[54:57]
	v_mfma_f32_16x16x32_bf16 v[38:41], v[138:141], v[162:165], v[38:41]
	v_mfma_f32_16x16x32_bf16 v[50:53], v[130:133], v[170:173], v[50:53]
	v_mfma_f32_16x16x32_bf16 v[34:37], v[138:141], v[170:173], v[34:37]
	v_mfma_f32_16x16x32_bf16 v[62:65], v[134:137], v[150:153], v[62:65]
	v_mfma_f32_16x16x32_bf16 v[46:49], v[142:145], v[150:153], v[46:49]
	v_mfma_f32_16x16x32_bf16 v[58:61], v[134:137], v[158:161], v[58:61]
	v_mfma_f32_16x16x32_bf16 v[42:45], v[142:145], v[158:161], v[42:45]
	v_mfma_f32_16x16x32_bf16 v[54:57], v[134:137], v[166:169], v[54:57]
	v_mfma_f32_16x16x32_bf16 v[38:41], v[142:145], v[166:169], v[38:41]
	v_mfma_f32_16x16x32_bf16 v[50:53], v[134:137], v[174:177], v[50:53]
	v_mfma_f32_16x16x32_bf16 v[34:37], v[142:145], v[174:177], v[34:37]
	s_barrier
	s_add_u32 s24, s26, 0x160000
	s_addc_u32 s25, s27, 0
	s_add_i32 s33, s38, s34
	s_mov_b32 m0, s33
	s_nop 0
	global_load_lds_dwordx4 v196, s[24:25]
	s_add_i32 m0, s33, 0x2000
	s_nop 0
	global_load_lds_dwordx4 v198, s[24:25]
	s_waitcnt vmcnt(6)
	s_barrier
; #define PG8_STAGE(bufoff, gbase, voff) do { _Pragma("unroll") for (int _i = 0; _i < 2; ++_i) \
;         __builtin_amdgcn_global_load_lds((const unsigned*)((const char*)(gbase) + (voff)[_i]), (LAS unsigned*)(lds + (bufoff) + ldsw + _i * 8192), 16, 0, 0); } while (0)
; #define PG8_LDA(dst, b, h) do { _Pragma("unroll") for (int m = 0; m < 4; ++m) _Pragma("unroll") for (int k = 0; k < 2; ++k) dst[m][k] = *(const LAS bf16x8*)(lds + PG8_SA(b, h) + aoff + m * 2048 + k * 1024); } while (0)
; #define PG8_LDB(dst, b, h) do { _Pragma("unroll") for (int n = 0; n < 2; ++n) _Pragma("unroll") for (int k = 0; k < 2; ++k) dst[n][k] = *(const LAS bf16x8*)(lds + PG8_SB(b, h) + boff + n * 2048 + k * 1024); } while (0)
; #define PG8_MMA(ai, bj, At, Bt) do { __builtin_amdgcn_s_setprio(1); _Pragma("unroll") for (int m = 0; m < 4; ++m) _Pragma("unroll") for (int n = 0; n < 2; ++n) _Pragma("unroll") for (int k = 0; k < 2; ++k) \
;         acc[ai][bj][m][n] = __builtin_amdgcn_mfma_f32_16x16x32_bf16(Bt[n][k], At[m][k], acc[ai][bj][m][n], 0, 0, 0); __builtin_amdgcn_s_setprio(0); } while (0)
; #define PG8_WAIT_V(n) asm volatile("s_waitcnt vmcnt(" #n ")" ::: "memory")
; #define PG8_WAIT_L(n) asm volatile("s_waitcnt lgkmcnt(" #n ")" ::: "memory")
; #define PG8_BAR __builtin_amdgcn_s_barrier()
; #define PG8_SCHED __builtin_amdgcn_sched_barrier(0)
; template <class Epi, class Sched, bool AREMAP>
; __device__ __forceinline__ void gemm_phase(LAS unsigned char* lds, const Gemm g, const Sched& S, const Epi& E, int wv) {
;     ...
;             PG8_STAGE(PG8_SB(0, 1), b2 + hstepB, voffB);
;             PG8_WAIT_V(6); PG8_BAR; PG8_MMA(1, 1, At, B1); PG8_BAR;
;             PG8_LDB(B0, 1, 0); PG8_SCHED; PG8_LDA(At, 1, 0); PG8_STAGE(PG8_SA(0, 1), a2 + hstepA, voffA);
;             PG8_WAIT_L(8); PG8_BAR; PG8_WAIT_L(0); PG8_MMA(0, 0, At, B0); PG8_BAR; PG8_SCHED;
;             PG8_LDB(B1, 1, 1); PG8_STAGE(PG8_SB(1, 0), b3, voffB);
;             PG8_BAR; PG8_WAIT_L(0); PG8_MMA(0, 1, At, B1); PG8_BAR;
	v_mfma_f32_16x16x32_bf16 v[30:33], v[178:181], v[146:149], v[30:33]
	v_mfma_f32_16x16x32_bf16 v[14:17], v[192:195], v[146:149], v[14:17]
	v_mfma_f32_16x16x32_bf16 v[26:29], v[178:181], v[154:157], v[26:29]
	v_mfma_f32_16x16x32_bf16 v[10:13], v[192:195], v[154:157], v[10:13]
	v_mfma_f32_16x16x32_bf16 v[22:25], v[178:181], v[162:165], v[22:25]
	v_mfma_f32_16x16x32_bf16 v[6:9], v[192:195], v[162:165], v[6:9]
	v_mfma_f32_16x16x32_bf16 v[18:21], v[178:181], v[170:173], v[18:21]
	v_mfma_f32_16x16x32_bf16 v[2:5], v[192:195], v[170:173], v[2:5]
	v_mfma_f32_16x16x32_bf16 v[30:33], v[182:185], v[150:153], v[30:33]
	v_mfma_f32_16x16x32_bf16 v[14:17], v[204:207], v[150:153], v[14:17]
	v_mfma_f32_16x16x32_bf16 v[26:29], v[182:185], v[158:161], v[26:29]
	v_mfma_f32_16x16x32_bf16 v[10:13], v[204:207], v[158:161], v[10:13]
	v_mfma_f32_16x16x32_bf16 v[22:25], v[182:185], v[166:169], v[22:25]
	v_mfma_f32_16x16x32_bf16 v[6:9], v[204:207], v[166:169], v[6:9]
	v_mfma_f32_16x16x32_bf16 v[18:21], v[182:185], v[174:177], v[18:21]
	v_mfma_f32_16x16x32_bf16 v[2:5], v[204:207], v[174:177], v[2:5]
	s_add_i32 s33, 0, 0x18000
	v_add_u32_e32 v1, s33, v250
	s_barrier
	ds_read_b128 v[130:133], v1
	ds_read_b128 v[134:137], v1 offset:1024
	ds_read_b128 v[138:141], v1 offset:2048
	ds_read_b128 v[142:145], v1 offset:3072
	s_add_u32 s24, s28, 0x160000
	s_addc_u32 s25, s29, 0
	s_mov_b32 m0, s37
	ds_read_b128 v[146:149], v252 offset:32768
	ds_read_b128 v[150:153], v252 offset:33792
	ds_read_b128 v[154:157], v252 offset:34816
	ds_read_b128 v[158:161], v252 offset:35840
	ds_read_b128 v[162:165], v252 offset:36864
	ds_read_b128 v[166:169], v252 offset:37888
	ds_read_b128 v[170:173], v252 offset:38912
	ds_read_b128 v[174:177], v252 offset:39936
	global_load_lds_dwordx4 v196, s[24:25]
	s_mov_b32 m0, s41
	s_nop 0
	global_load_lds_dwordx4 v198, s[24:25]
	s_waitcnt lgkmcnt(8)
	s_barrier
	s_waitcnt lgkmcnt(0)
	s_waitcnt lgkmcnt(0)
	v_mfma_f32_16x16x32_bf16 v[126:129], v[130:133], v[146:149], v[126:129]
	v_mfma_f32_16x16x32_bf16 v[110:113], v[138:141], v[146:149], v[110:113]
	v_mfma_f32_16x16x32_bf16 v[122:125], v[130:133], v[154:157], v[122:125]
	v_mfma_f32_16x16x32_bf16 v[106:109], v[138:141], v[154:157], v[106:109]
	v_mfma_f32_16x16x32_bf16 v[118:121], v[130:133], v[162:165], v[118:121]
	v_mfma_f32_16x16x32_bf16 v[102:105], v[138:141], v[162:165], v[102:105]
	v_mfma_f32_16x16x32_bf16 v[114:117], v[130:133], v[170:173], v[114:117]
	v_mfma_f32_16x16x32_bf16 v[98:101], v[138:141], v[170:173], v[98:101]
	v_mfma_f32_16x16x32_bf16 v[126:129], v[134:137], v[150:153], v[126:129]
	v_mfma_f32_16x16x32_bf16 v[110:113], v[142:145], v[150:153], v[110:113]
	v_mfma_f32_16x16x32_bf16 v[122:125], v[134:137], v[158:161], v[122:125]
	v_mfma_f32_16x16x32_bf16 v[106:109], v[142:145], v[158:161], v[106:109]
	v_mfma_f32_16x16x32_bf16 v[118:121], v[134:137], v[166:169], v[118:121]
	v_mfma_f32_16x16x32_bf16 v[102:105], v[142:145], v[166:169], v[102:105]
	v_mfma_f32_16x16x32_bf16 v[114:117], v[134:137], v[174:177], v[114:117]
	v_mfma_f32_16x16x32_bf16 v[98:101], v[142:145], v[174:177], v[98:101]
	s_barrier
	s_add_i32 s28, 0, 0x1c000
	s_add_i32 s24, s33, s34
	v_add_u32_e32 v1, s28, v250
	s_mov_b32 m0, s24
	ds_read_b128 v[178:181], v1
	ds_read_b128 v[182:185], v1 offset:1024
	ds_read_b128 v[192:195], v1 offset:2048
	ds_read_b128 v[204:207], v1 offset:3072
	global_load_lds_dwordx4 v196, s[80:81]
	s_add_i32 m0, s24, 0x2000
	s_nop 0
	global_load_lds_dwordx4 v198, s[80:81]
	s_barrier
	s_waitcnt lgkmcnt(0)
	s_waitcnt lgkmcnt(0)
	v_mfma_f32_16x16x32_bf16 v[94:97], v[178:181], v[146:149], v[94:97]
	v_mfma_f32_16x16x32_bf16 v[78:81], v[192:195], v[146:149], v[78:81]
	v_mfma_f32_16x16x32_bf16 v[90:93], v[178:181], v[154:157], v[90:93]
	v_mfma_f32_16x16x32_bf16 v[74:77], v[192:195], v[154:157], v[74:77]
	v_mfma_f32_16x16x32_bf16 v[86:89], v[178:181], v[162:165], v[86:89]
	v_mfma_f32_16x16x32_bf16 v[70:73], v[192:195], v[162:165], v[70:73]
	v_mfma_f32_16x16x32_bf16 v[82:85], v[178:181], v[170:173], v[82:85]
	v_mfma_f32_16x16x32_bf16 v[66:69], v[192:195], v[170:173], v[66:69]
	v_mfma_f32_16x16x32_bf16 v[94:97], v[182:185], v[150:153], v[94:97]
	v_mfma_f32_16x16x32_bf16 v[78:81], v[204:207], v[150:153], v[78:81]
	v_mfma_f32_16x16x32_bf16 v[90:93], v[182:185], v[158:161], v[90:93]
	v_mfma_f32_16x16x32_bf16 v[74:77], v[204:207], v[158:161], v[74:77]
	v_mfma_f32_16x16x32_bf16 v[86:89], v[182:185], v[166:169], v[86:89]
	v_mfma_f32_16x16x32_bf16 v[70:73], v[204:207], v[166:169], v[70:73]
	v_mfma_f32_16x16x32_bf16 v[82:85], v[182:185], v[174:177], v[82:85]
	v_mfma_f32_16x16x32_bf16 v[66:69], v[204:207], v[174:177], v[66:69]
	s_mov_b32 m0, s46
	s_barrier
; #define PG8_STAGE(bufoff, gbase, voff) do { _Pragma("unroll") for (int _i = 0; _i < 2; ++_i) \
;         __builtin_amdgcn_global_load_lds((const unsigned*)((const char*)(gbase) + (voff)[_i]), (LAS unsigned*)(lds + (bufoff) + ldsw + _i * 8192), 16, 0, 0); } while (0)
; #define PG8_LDA(dst, b, h) do { _Pragma("unroll") for (int m = 0; m < 4; ++m) _Pragma("unroll") for (int k = 0; k < 2; ++k) dst[m][k] = *(const LAS bf16x8*)(lds + PG8_SA(b, h) + aoff + m * 2048 + k * 1024); } while (0)
; #define PG8_MMA(ai, bj, At, Bt) do { __builtin_amdgcn_s_setprio(1); _Pragma("unroll") for (int m = 0; m < 4; ++m) _Pragma("unroll") for (int n = 0; n < 2; ++n) _Pragma("unroll") for (int k = 0; k < 2; ++k) \
;         acc[ai][bj][m][n] = __builtin_amdgcn_mfma_f32_16x16x32_bf16(Bt[n][k], At[m][k], acc[ai][bj][m][n], 0, 0, 0); __builtin_amdgcn_s_setprio(0); } while (0)
; #define PG8_WAIT_V(n) asm volatile("s_waitcnt vmcnt(" #n ")" ::: "memory")
; #define PG8_WAIT_L(n) asm volatile("s_waitcnt lgkmcnt(" #n ")" ::: "memory")
; #define PG8_BAR __builtin_amdgcn_s_barrier()
; #define PG8_SCHED __builtin_amdgcn_sched_barrier(0)
; template <class Epi, class Sched, bool AREMAP>
; __device__ __forceinline__ void gemm_phase(LAS unsigned char* lds, const Gemm g, const Sched& S, const Epi& E, int wv) {
;     ...
;             PG8_LDA(At, 1, 1); PG8_STAGE(PG8_SA(1, 0), a3, voffA);
;             PG8_BAR; PG8_WAIT_L(0); PG8_MMA(1, 0, At, B0); PG8_BAR; PG8_SCHED;
;             PG8_STAGE(PG8_SB(1, 1), b3 + hstepB, voffB);
;             PG8_WAIT_V(6); PG8_BAR; PG8_MMA(1, 1, At, B1); PG8_BAR;
;         }
;     __device__ __forceinline__ void operator()(const f32x4 (&acc)[2][2][4][2], const Unit& u, int wr, int wc, int fr, int fq) const {
;         const int row0 = u.pm * BM + wr * 64 + fr, col0 = u.pn * BM + wc * 32 + 4 * fq;
;         const float* gv = gate + (size_t)(u.pm >> 3) * 12288 + col0;
; #pragma unroll
;         for (int ai = 0; ai < 2; ++ai) {
;             float mu[4], rs[4];
; #pragma unroll
;             for (int m = 0; m < 4; ++m) { mu[m] = 0.f; rs[m] = 1.f;
;                 if (stats) { const float* sp = stats + (size_t)(row0 + ai * HALF + m * 16) * 2; mu[m] = sp[0]; rs[m] = sp[1]; } }
	ds_read_b128 v[146:149], v252 offset:49152
	ds_read_b128 v[150:153], v252 offset:50176
	ds_read_b128 v[154:157], v252 offset:51200
	ds_read_b128 v[158:161], v252 offset:52224
	ds_read_b128 v[162:165], v252 offset:53248
	ds_read_b128 v[166:169], v252 offset:54272
	ds_read_b128 v[170:173], v252 offset:55296
	ds_read_b128 v[174:177], v252 offset:56320
	global_load_lds_dwordx4 v196, s[96:97]
	s_mov_b32 m0, s47
	s_nop 0
	global_load_lds_dwordx4 v198, s[96:97]
	s_barrier
	s_waitcnt lgkmcnt(0)
	s_waitcnt lgkmcnt(0)
	v_mfma_f32_16x16x32_bf16 v[62:65], v[130:133], v[146:149], v[62:65]
	v_mfma_f32_16x16x32_bf16 v[46:49], v[138:141], v[146:149], v[46:49]
	v_mfma_f32_16x16x32_bf16 v[58:61], v[130:133], v[154:157], v[58:61]
	v_mfma_f32_16x16x32_bf16 v[42:45], v[138:141], v[154:157], v[42:45]
	v_mfma_f32_16x16x32_bf16 v[54:57], v[130:133], v[162:165], v[54:57]
	v_mfma_f32_16x16x32_bf16 v[38:41], v[138:141], v[162:165], v[38:41]
	v_mfma_f32_16x16x32_bf16 v[50:53], v[130:133], v[170:173], v[50:53]
	v_mfma_f32_16x16x32_bf16 v[34:37], v[138:141], v[170:173], v[34:37]
	v_mfma_f32_16x16x32_bf16 v[62:65], v[134:137], v[150:153], v[62:65]
	v_mfma_f32_16x16x32_bf16 v[46:49], v[142:145], v[150:153], v[46:49]
	v_mfma_f32_16x16x32_bf16 v[58:61], v[134:137], v[158:161], v[58:61]
	v_mfma_f32_16x16x32_bf16 v[42:45], v[142:145], v[158:161], v[42:45]
	v_mfma_f32_16x16x32_bf16 v[54:57], v[134:137], v[166:169], v[54:57]
	v_mfma_f32_16x16x32_bf16 v[38:41], v[142:145], v[166:169], v[38:41]
	v_mfma_f32_16x16x32_bf16 v[50:53], v[134:137], v[174:177], v[50:53]
	v_mfma_f32_16x16x32_bf16 v[34:37], v[142:145], v[174:177], v[34:37]
	s_barrier
	s_add_u32 s24, s26, 0x160080
	s_addc_u32 s25, s27, 0
	s_add_i32 s26, s28, s34
	s_mov_b32 m0, s26
	s_nop 0
	global_load_lds_dwordx4 v196, s[24:25]
	s_add_i32 m0, s26, 0x2000
	s_nop 0
	global_load_lds_dwordx4 v198, s[24:25]
	s_waitcnt vmcnt(6)
	s_barrier
	v_mfma_f32_16x16x32_bf16 v[30:33], v[178:181], v[146:149], v[30:33]
	v_mfma_f32_16x16x32_bf16 v[14:17], v[192:195], v[146:149], v[14:17]
	v_mfma_f32_16x16x32_bf16 v[26:29], v[178:181], v[154:157], v[26:29]
	v_mfma_f32_16x16x32_bf16 v[10:13], v[192:195], v[154:157], v[10:13]
	v_mfma_f32_16x16x32_bf16 v[22:25], v[178:181], v[162:165], v[22:25]
	v_mfma_f32_16x16x32_bf16 v[6:9], v[192:195], v[162:165], v[6:9]
	v_mfma_f32_16x16x32_bf16 v[18:21], v[178:181], v[170:173], v[18:21]
	v_mfma_f32_16x16x32_bf16 v[2:5], v[192:195], v[170:173], v[2:5]
	v_mfma_f32_16x16x32_bf16 v[30:33], v[182:185], v[150:153], v[30:33]
	v_mfma_f32_16x16x32_bf16 v[14:17], v[204:207], v[150:153], v[14:17]
	v_mfma_f32_16x16x32_bf16 v[26:29], v[182:185], v[158:161], v[26:29]
	v_mfma_f32_16x16x32_bf16 v[10:13], v[204:207], v[158:161], v[10:13]
	v_mfma_f32_16x16x32_bf16 v[22:25], v[182:185], v[166:169], v[22:25]
	v_mfma_f32_16x16x32_bf16 v[6:9], v[204:207], v[166:169], v[6:9]
	v_mfma_f32_16x16x32_bf16 v[18:21], v[182:185], v[174:177], v[18:21]
	v_mfma_f32_16x16x32_bf16 v[2:5], v[204:207], v[174:177], v[2:5]
	s_add_i32 s67, s67, 2
	s_add_u32 s65, s65, 0x100
	s_addc_u32 s66, s66, 0
	s_cmpk_gt_u32 s67, 0x55
	s_mov_b64 s[24:25], s[2:3]
	s_barrier
	s_cbranch_scc0 .LBB0_674
	v_lshl_add_u32 v212, s62, 8, v249
	v_cndmask_b32_e64 v1, 0, 1, s[20:21]
	v_mov_b32_e32 v216, 1.0
	v_cmp_ne_u32_e64 s[2:3], 1, v1
	s_andn2_b64 vcc, exec, s[20:21]
	v_ashrrev_i32_e32 v213, 31, v212
	s_cbranch_vccnz .LBB0_677
	v_lshl_add_u64 v[130:131], v[212:213], 3, s[18:19]
	global_load_dwordx2 v[134:135], v[130:131], off
	s_branch .LBB0_678
